# P4b epilogue: hoisted the 64 serialized residual x loads (issued back-to-back into the dead accumulator AGPRs, one wait) and removed the per-element vmcnt(0) ladder
# speedup vs baseline: 1.0677x; 1.0530x over previous
; __device__ __forceinline__ u16 f2bf(float f) { return (u16)(pack2(f, f) & 0xffffu); }
; __device__ __forceinline__ float sum32(float v) { v = dpp_row_sum16(v); v += __shfl_xor(v, 16); return v; }
; __device__ __forceinline__ int rowmap(int e, int lane) { return (e & 3) + 8 * (e >> 2) + 4 * (lane >> 5); }
; __device__ __forceinline__ void phase4b(const Params& p, char* smem) {
;     ...
; #pragma unroll
;     for (int i = 0; i < 2; i++)
; #pragma unroll
;       for (int e = 0; e < 16; e++) {
;         const int row = m0 + wm * 64 + i * 32 + rowmap(e, lane);
;         const float* xr = xrow(p, row);
;         float sq = 0.f;
; #pragma unroll
;         for (int j = 0; j < 2; j++) {
;           const int col = n0 + wn * 64 + j * 32 + (lane & 31);
;           float v = acc[i][j][e] + xr[col];
;           X1[(size_t)row * 1024 + col] = v;
;           ((u16*)smem)[(row - m0) * 136 + (col - n0)] = f2bf(v);
;           sq += v * v;
;         }
;         sq = sum32(sq);
;         if ((lane & 31) == 0) atomicAdd(&SSQ1[row], sq);
;       }
.LBB0_1297:
	s_nop 7
	v_accvgpr_read_b32 v48, a48
	v_accvgpr_read_b32 v49, a49
	v_accvgpr_read_b32 v50, a50
	v_accvgpr_read_b32 v51, a51
	v_accvgpr_read_b32 v52, a52
	v_accvgpr_read_b32 v53, a53
	v_accvgpr_read_b32 v54, a54
	v_accvgpr_read_b32 v55, a55
	v_accvgpr_read_b32 v56, a56
	v_accvgpr_read_b32 v57, a57
	v_accvgpr_read_b32 v58, a58
	v_accvgpr_read_b32 v59, a59
	v_accvgpr_read_b32 v60, a60
	v_accvgpr_read_b32 v61, a61
	v_accvgpr_read_b32 v62, a62
	v_accvgpr_read_b32 v63, a63
	v_accvgpr_read_b32 v32, a32
	v_accvgpr_read_b32 v33, a33
	v_accvgpr_read_b32 v34, a34
	v_accvgpr_read_b32 v35, a35
	v_accvgpr_read_b32 v36, a36
	v_accvgpr_read_b32 v37, a37
	v_accvgpr_read_b32 v38, a38
	v_accvgpr_read_b32 v39, a39
	v_accvgpr_read_b32 v40, a40
	v_accvgpr_read_b32 v41, a41
	v_accvgpr_read_b32 v42, a42
	v_accvgpr_read_b32 v43, a43
	v_accvgpr_read_b32 v44, a44
	v_accvgpr_read_b32 v45, a45
	v_accvgpr_read_b32 v46, a46
	v_accvgpr_read_b32 v47, a47
	v_accvgpr_read_b32 v16, a16
	v_accvgpr_read_b32 v17, a17
	v_accvgpr_read_b32 v18, a18
	v_accvgpr_read_b32 v19, a19
	v_accvgpr_read_b32 v20, a20
	v_accvgpr_read_b32 v21, a21
	v_accvgpr_read_b32 v22, a22
	v_accvgpr_read_b32 v23, a23
	v_accvgpr_read_b32 v24, a24
	v_accvgpr_read_b32 v25, a25
	v_accvgpr_read_b32 v26, a26
	v_accvgpr_read_b32 v27, a27
	v_accvgpr_read_b32 v28, a28
	v_accvgpr_read_b32 v29, a29
	v_accvgpr_read_b32 v30, a30
	v_accvgpr_read_b32 v31, a31
	v_accvgpr_read_b32 v0, a0
	v_accvgpr_read_b32 v1, a1
	v_accvgpr_read_b32 v2, a2
	v_accvgpr_read_b32 v3, a3
	v_accvgpr_read_b32 v4, a4
	v_accvgpr_read_b32 v5, a5
	v_accvgpr_read_b32 v6, a6
	v_accvgpr_read_b32 v7, a7
	v_accvgpr_read_b32 v8, a8
	v_accvgpr_read_b32 v9, a9
	v_accvgpr_read_b32 v10, a10
	v_accvgpr_read_b32 v11, a11
	v_accvgpr_read_b32 v12, a12
	v_accvgpr_read_b32 v13, a13
	v_accvgpr_read_b32 v14, a14
	v_accvgpr_read_b32 v15, a15
	v_add_u32_e32 v135, s6, v105
	v_or_b32_e32 v94, v135, v117
	v_cmp_le_i32_e32 vcc, s14, v94
	v_mov_b32_e32 v64, s42
	v_mov_b32_e32 v137, s40
	v_mov_b32_e32 v95, 0
	v_cndmask_b32_e32 v146, v137, v64, vcc
	v_mov_b32_e32 v64, s43
	v_mov_b32_e32 v137, s41
	v_or_b32_e32 v148, 32, v135
	v_cndmask_b32_e32 v147, v137, v64, vcc
	v_mov_b32_e32 v64, 0xfc000000
	v_cndmask_b32_e32 v92, 0, v64, vcc
	v_cndmask_b32_e64 v93, 0, -1, vcc
	v_lshl_add_u64 v[146:147], v[92:93], 0, v[146:147]
	v_or_b32_e32 v64, s45, v107
	v_lshlrev_b32_e32 v64, 2, v64
	v_lshl_add_u64 v[146:147], v[64:65], 0, v[146:147]
	v_add_lshl_u32 v94, v135, v117, 12
	v_lshl_add_u64 v[92:93], v[94:95], 0, v[146:147]
	global_load_dword a48, v[92:93], off
	global_load_dword a32, v[92:93], off offset:128
	v_add_lshl_u32 v94, v135, v120, 12
	v_lshl_add_u64 v[92:93], v[94:95], 0, v[146:147]
	global_load_dword a49, v[92:93], off
	global_load_dword a33, v[92:93], off offset:128
	v_add_lshl_u32 v94, v135, v121, 12
	v_lshl_add_u64 v[92:93], v[94:95], 0, v[146:147]
	global_load_dword a50, v[92:93], off
	global_load_dword a34, v[92:93], off offset:128
	v_add_lshl_u32 v94, v135, v122, 12
	v_lshl_add_u64 v[92:93], v[94:95], 0, v[146:147]
	global_load_dword a51, v[92:93], off
	global_load_dword a35, v[92:93], off offset:128
	v_add_lshl_u32 v94, v135, v123, 12
	v_lshl_add_u64 v[92:93], v[94:95], 0, v[146:147]
	global_load_dword a52, v[92:93], off
	global_load_dword a36, v[92:93], off offset:128
	v_add_lshl_u32 v94, v135, v124, 12
	v_lshl_add_u64 v[92:93], v[94:95], 0, v[146:147]
	global_load_dword a53, v[92:93], off
	global_load_dword a37, v[92:93], off offset:128
	v_add_lshl_u32 v94, v135, v125, 12
	v_lshl_add_u64 v[92:93], v[94:95], 0, v[146:147]
	global_load_dword a54, v[92:93], off
	global_load_dword a38, v[92:93], off offset:128
	v_add_lshl_u32 v94, v135, v126, 12
	v_lshl_add_u64 v[92:93], v[94:95], 0, v[146:147]
	global_load_dword a55, v[92:93], off
	global_load_dword a39, v[92:93], off offset:128
	v_add_lshl_u32 v94, v135, v127, 12
	v_lshl_add_u64 v[92:93], v[94:95], 0, v[146:147]
	global_load_dword a56, v[92:93], off
	global_load_dword a40, v[92:93], off offset:128
	v_add_lshl_u32 v94, v135, v128, 12
	v_lshl_add_u64 v[92:93], v[94:95], 0, v[146:147]
	global_load_dword a57, v[92:93], off
	global_load_dword a41, v[92:93], off offset:128
	v_add_lshl_u32 v94, v135, v129, 12
	v_lshl_add_u64 v[92:93], v[94:95], 0, v[146:147]
	global_load_dword a58, v[92:93], off
	global_load_dword a42, v[92:93], off offset:128
	v_add_lshl_u32 v94, v135, v130, 12
	v_lshl_add_u64 v[92:93], v[94:95], 0, v[146:147]
	global_load_dword a59, v[92:93], off
	global_load_dword a43, v[92:93], off offset:128
	v_add_lshl_u32 v94, v135, v131, 12
	v_lshl_add_u64 v[92:93], v[94:95], 0, v[146:147]
	global_load_dword a60, v[92:93], off
	global_load_dword a44, v[92:93], off offset:128
	v_add_lshl_u32 v94, v135, v132, 12
	v_lshl_add_u64 v[92:93], v[94:95], 0, v[146:147]
	global_load_dword a61, v[92:93], off
	global_load_dword a45, v[92:93], off offset:128
	v_add_lshl_u32 v94, v135, v133, 12
	v_lshl_add_u64 v[92:93], v[94:95], 0, v[146:147]
	global_load_dword a62, v[92:93], off
	global_load_dword a46, v[92:93], off offset:128
	v_add_lshl_u32 v94, v135, v134, 12
	v_lshl_add_u64 v[92:93], v[94:95], 0, v[146:147]
	global_load_dword a63, v[92:93], off
	global_load_dword a47, v[92:93], off offset:128
	v_add_lshl_u32 v94, v148, v117, 12
	v_lshl_add_u64 v[92:93], v[94:95], 0, v[146:147]
	global_load_dword a16, v[92:93], off
	global_load_dword a0, v[92:93], off offset:128
	v_add_lshl_u32 v94, v148, v120, 12
	v_lshl_add_u64 v[92:93], v[94:95], 0, v[146:147]
	global_load_dword a17, v[92:93], off
	global_load_dword a1, v[92:93], off offset:128
	v_add_lshl_u32 v94, v148, v121, 12
	v_lshl_add_u64 v[92:93], v[94:95], 0, v[146:147]
; __device__ __forceinline__ u16 f2bf(float f) { return (u16)(pack2(f, f) & 0xffffu); }
; __device__ __forceinline__ float sum32(float v) { v = dpp_row_sum16(v); v += __shfl_xor(v, 16); return v; }
; __device__ __forceinline__ int rowmap(int e, int lane) { return (e & 3) + 8 * (e >> 2) + 4 * (lane >> 5); }
; __device__ __forceinline__ void phase4b(const Params& p, char* smem) {
;     ...
; #pragma unroll
;     for (int i = 0; i < 2; i++)
; #pragma unroll
;       for (int e = 0; e < 16; e++) {
;         const int row = m0 + wm * 64 + i * 32 + rowmap(e, lane);
;         const float* xr = xrow(p, row);
;         float sq = 0.f;
; #pragma unroll
;         for (int j = 0; j < 2; j++) {
;           const int col = n0 + wn * 64 + j * 32 + (lane & 31);
;           float v = acc[i][j][e] + xr[col];
;           X1[(size_t)row * 1024 + col] = v;
;           ((u16*)smem)[(row - m0) * 136 + (col - n0)] = f2bf(v);
;           sq += v * v;
;         }
;         sq = sum32(sq);
;         if ((lane & 31) == 0) atomicAdd(&SSQ1[row], sq);
;       }
	global_load_dword a18, v[92:93], off
	global_load_dword a2, v[92:93], off offset:128
	v_add_lshl_u32 v94, v148, v122, 12
	v_lshl_add_u64 v[92:93], v[94:95], 0, v[146:147]
	global_load_dword a19, v[92:93], off
	global_load_dword a3, v[92:93], off offset:128
	v_add_lshl_u32 v94, v148, v123, 12
	v_lshl_add_u64 v[92:93], v[94:95], 0, v[146:147]
	global_load_dword a20, v[92:93], off
	global_load_dword a4, v[92:93], off offset:128
	v_add_lshl_u32 v94, v148, v124, 12
	v_lshl_add_u64 v[92:93], v[94:95], 0, v[146:147]
	global_load_dword a21, v[92:93], off
	global_load_dword a5, v[92:93], off offset:128
	v_add_lshl_u32 v94, v148, v125, 12
	v_lshl_add_u64 v[92:93], v[94:95], 0, v[146:147]
	global_load_dword a22, v[92:93], off
	global_load_dword a6, v[92:93], off offset:128
	v_add_lshl_u32 v94, v148, v126, 12
	v_lshl_add_u64 v[92:93], v[94:95], 0, v[146:147]
	global_load_dword a23, v[92:93], off
	global_load_dword a7, v[92:93], off offset:128
	v_add_lshl_u32 v94, v148, v127, 12
	v_lshl_add_u64 v[92:93], v[94:95], 0, v[146:147]
	global_load_dword a24, v[92:93], off
	global_load_dword a8, v[92:93], off offset:128
	v_add_lshl_u32 v94, v148, v128, 12
	v_lshl_add_u64 v[92:93], v[94:95], 0, v[146:147]
	global_load_dword a25, v[92:93], off
	global_load_dword a9, v[92:93], off offset:128
	v_add_lshl_u32 v94, v148, v129, 12
	v_lshl_add_u64 v[92:93], v[94:95], 0, v[146:147]
	global_load_dword a26, v[92:93], off
	global_load_dword a10, v[92:93], off offset:128
	v_add_lshl_u32 v94, v148, v130, 12
	v_lshl_add_u64 v[92:93], v[94:95], 0, v[146:147]
	global_load_dword a27, v[92:93], off
	global_load_dword a11, v[92:93], off offset:128
	v_add_lshl_u32 v94, v148, v131, 12
	v_lshl_add_u64 v[92:93], v[94:95], 0, v[146:147]
	global_load_dword a28, v[92:93], off
	global_load_dword a12, v[92:93], off offset:128
	v_add_lshl_u32 v94, v148, v132, 12
	v_lshl_add_u64 v[92:93], v[94:95], 0, v[146:147]
	global_load_dword a29, v[92:93], off
	global_load_dword a13, v[92:93], off offset:128
	v_add_lshl_u32 v94, v148, v133, 12
	v_lshl_add_u64 v[92:93], v[94:95], 0, v[146:147]
	global_load_dword a30, v[92:93], off
	global_load_dword a14, v[92:93], off offset:128
	v_add_lshl_u32 v94, v148, v134, 12
	v_lshl_add_u64 v[92:93], v[94:95], 0, v[146:147]
	global_load_dword a31, v[92:93], off
	global_load_dword a15, v[92:93], off offset:128
	s_waitcnt vmcnt(0)
	v_add_u32_e32 v135, s6, v105
	v_or_b32_e32 v94, v135, v117
	v_add_u32_e32 v64, 0xffffc000, v94
	v_cmp_gt_i32_e32 vcc, s14, v94
	v_ashrrev_i32_e32 v95, 31, v94
	v_mov_b32_e32 v137, s41
	v_cndmask_b32_e32 v92, v64, v94, vcc
	v_mov_b32_e32 v64, s43
	v_cndmask_b32_e32 v93, 0, v95, vcc
	v_cndmask_b32_e32 v147, v64, v137, vcc
	v_mov_b32_e32 v64, s42
	v_mov_b32_e32 v137, s40
	v_cndmask_b32_e32 v146, v64, v137, vcc
	v_lshlrev_b64 v[92:93], 12, v[92:93]
	v_or_b32_e32 v64, s45, v107
	v_lshl_add_u64 v[146:147], v[146:147], 0, v[92:93]
	v_lshlrev_b32_e32 v64, 2, v64
	v_lshl_add_u64 v[92:93], v[146:147], 0, v[64:65]
	v_accvgpr_read_b32 v137, a48
	v_lshlrev_b64 v[148:149], 12, v[94:95]
	v_add_u32_e32 v92, s45, v107
	v_lshl_add_u64 v[148:149], s[78:79], 0, v[148:149]
	v_mov_b32_e32 v93, v65
	v_lshlrev_b32_e32 v92, 2, v92
	v_lshl_add_u64 v[150:151], v[148:149], 0, v[64:65]
	v_lshl_add_u64 v[146:147], v[146:147], 0, v[92:93]
	v_lshl_add_u64 v[148:149], v[148:149], 0, v[92:93]
	v_add_f32_e32 v48, v48, v137
	global_store_dword v[150:151], v48, off
	v_accvgpr_read_b32 v137, a32
	v_cvt_pk_bf16_f32 v150, v48, s0
	v_subrev_u32_e32 v146, s6, v94
	v_mad_u64_u32 v[146:147], s[8:9], v146, s15, v[68:69]
	ds_write_b16 v146, v150
	v_add_f32_e32 v137, v32, v137
	v_mul_f32_e32 v32, v137, v137
	v_fmac_f32_e32 v32, v48, v48
	global_store_dword v[148:149], v137, off offset:128
	v_cvt_pk_bf16_f32 v137, v137, s0
	v_add_f32_dpp v32, v32, v32 quad_perm:[1,0,3,2] row_mask:0xf bank_mask:0xf bound_ctrl:1
	ds_write_b16 v146, v137 offset:64
	s_nop 0
	v_add_f32_dpp v32, v32, v32 quad_perm:[2,3,0,1] row_mask:0xf bank_mask:0xf bound_ctrl:1
	s_nop 1
	v_add_f32_dpp v32, v32, v32 row_half_mirror row_mask:0xf bank_mask:0xf bound_ctrl:1
	s_nop 1
	v_add_f32_dpp v32, v32, v32 row_mirror row_mask:0xf bank_mask:0xf bound_ctrl:1
	ds_bpermute_b32 v48, v118, v32
	s_and_saveexec_b64 s[8:9], s[4:5]
	s_cbranch_execz .LBB0_1299
	s_waitcnt lgkmcnt(0)
	v_add_f32_e32 v32, v32, v48
	v_lshl_add_u64 v[94:95], v[94:95], 2, s[94:95]
	global_atomic_add_f32 v[94:95], v32, off
.LBB0_1299:
	s_or_b64 exec, exec, s[8:9]
	v_or_b32_e32 v94, v135, v120
	v_add_u32_e32 v32, 0xffffc000, v94
	v_cmp_gt_i32_e32 vcc, s14, v94
	v_ashrrev_i32_e32 v95, 31, v94
	s_waitcnt lgkmcnt(0)
	v_mov_b32_e32 v48, s41
	v_cndmask_b32_e32 v146, v32, v94, vcc
	v_mov_b32_e32 v32, s43
	v_cndmask_b32_e32 v147, 0, v95, vcc
	v_cndmask_b32_e32 v149, v32, v48, vcc
	v_mov_b32_e32 v32, s42
	v_mov_b32_e32 v48, s40
	v_cndmask_b32_e32 v148, v32, v48, vcc
	v_lshlrev_b64 v[146:147], 12, v[146:147]
	v_lshl_add_u64 v[146:147], v[148:149], 0, v[146:147]
	v_lshl_add_u64 v[148:149], v[146:147], 0, v[64:65]
	v_accvgpr_read_b32 v32, a49
	v_lshlrev_b64 v[148:149], 12, v[94:95]
	v_lshl_add_u64 v[148:149], s[78:79], 0, v[148:149]
	v_lshl_add_u64 v[150:151], v[148:149], 0, v[64:65]
	v_add_f32_e32 v32, v49, v32
	global_store_dword v[150:151], v32, off
	v_lshl_add_u64 v[48:49], v[146:147], 0, v[92:93]
	v_accvgpr_read_b32 v137, a33
	v_subrev_u32_e32 v48, s6, v94
	v_mad_u64_u32 v[48:49], s[8:9], v48, s15, v[68:69]
	v_cvt_pk_bf16_f32 v146, v32, s0
	ds_write_b16 v48, v146
	v_lshl_add_u64 v[146:147], v[148:149], 0, v[92:93]
	v_add_f32_e32 v49, v33, v137
	v_mul_f32_e32 v33, v49, v49
	v_fmac_f32_e32 v33, v32, v32
	global_store_dword v[146:147], v49, off offset:128
	v_cvt_pk_bf16_f32 v49, v49, s0
	v_add_f32_dpp v32, v33, v33 quad_perm:[1,0,3,2] row_mask:0xf bank_mask:0xf bound_ctrl:1
	ds_write_b16 v48, v49 offset:64
	s_nop 0
	v_add_f32_dpp v32, v32, v32 quad_perm:[2,3,0,1] row_mask:0xf bank_mask:0xf bound_ctrl:1
	s_nop 1
	v_add_f32_dpp v32, v32, v32 row_half_mirror row_mask:0xf bank_mask:0xf bound_ctrl:1
	s_nop 1
	v_add_f32_dpp v32, v32, v32 row_mirror row_mask:0xf bank_mask:0xf bound_ctrl:1
	ds_bpermute_b32 v33, v118, v32
	s_and_saveexec_b64 s[8:9], s[4:5]
	s_cbranch_execz .LBB0_1301
	s_waitcnt lgkmcnt(0)
	v_add_f32_e32 v48, v32, v33
	v_lshl_add_u64 v[32:33], v[94:95], 2, s[94:95]
	global_atomic_add_f32 v[32:33], v48, off
; __device__ __forceinline__ u16 f2bf(float f) { return (u16)(pack2(f, f) & 0xffffu); }
; __device__ __forceinline__ float sum32(float v) { v = dpp_row_sum16(v); v += __shfl_xor(v, 16); return v; }
; __device__ __forceinline__ int rowmap(int e, int lane) { return (e & 3) + 8 * (e >> 2) + 4 * (lane >> 5); }
; __device__ __forceinline__ void phase4b(const Params& p, char* smem) {
;     ...
; #pragma unroll
;     for (int i = 0; i < 2; i++)
; #pragma unroll
;       for (int e = 0; e < 16; e++) {
;         const int row = m0 + wm * 64 + i * 32 + rowmap(e, lane);
;         const float* xr = xrow(p, row);
;         float sq = 0.f;
; #pragma unroll
;         for (int j = 0; j < 2; j++) {
;           const int col = n0 + wn * 64 + j * 32 + (lane & 31);
;           float v = acc[i][j][e] + xr[col];
;           X1[(size_t)row * 1024 + col] = v;
;           ((u16*)smem)[(row - m0) * 136 + (col - n0)] = f2bf(v);
;           sq += v * v;
;         }
;         sq = sum32(sq);
;         if ((lane & 31) == 0) atomicAdd(&SSQ1[row], sq);
;       }
.LBB0_1301:
	s_or_b64 exec, exec, s[8:9]
	v_or_b32_e32 v32, v135, v121
	v_add_u32_e32 v48, 0xffffc000, v32
	s_waitcnt lgkmcnt(0)
	v_ashrrev_i32_e32 v33, 31, v32
	v_cmp_gt_i32_e32 vcc, s14, v32
	v_mov_b32_e32 v93, s43
	v_mov_b32_e32 v94, s41
	v_cndmask_b32_e32 v49, 0, v33, vcc
	v_cndmask_b32_e32 v48, v48, v32, vcc
	v_cndmask_b32_e32 v95, v93, v94, vcc
	v_mov_b32_e32 v93, s42
	v_mov_b32_e32 v94, s40
	v_cndmask_b32_e32 v94, v93, v94, vcc
	v_lshlrev_b64 v[48:49], 12, v[48:49]
	v_lshl_add_u64 v[48:49], v[94:95], 0, v[48:49]
	v_lshl_add_u64 v[94:95], v[48:49], 0, v[64:65]
	v_accvgpr_read_b32 v137, a50
	v_lshlrev_b64 v[94:95], 12, v[32:33]
	v_lshl_add_u64 v[94:95], s[78:79], 0, v[94:95]
	v_mov_b32_e32 v93, v65
	v_lshl_add_u64 v[146:147], v[94:95], 0, v[64:65]
	v_lshl_add_u64 v[48:49], v[48:49], 0, v[92:93]
	v_lshl_add_u64 v[94:95], v[94:95], 0, v[92:93]
	v_add_f32_e32 v50, v50, v137
	global_store_dword v[146:147], v50, off
	v_accvgpr_read_b32 v48, a34
	v_subrev_u32_e32 v49, s6, v32
	v_mad_u64_u32 v[146:147], s[8:9], v49, s15, v[68:69]
	v_cvt_pk_bf16_f32 v137, v50, s0
	ds_write_b16 v146, v137
	v_add_f32_e32 v49, v34, v48
	v_mul_f32_e32 v34, v49, v49
	v_fmac_f32_e32 v34, v50, v50
	global_store_dword v[94:95], v49, off offset:128
	v_cvt_pk_bf16_f32 v49, v49, s0
	v_add_f32_dpp v34, v34, v34 quad_perm:[1,0,3,2] row_mask:0xf bank_mask:0xf bound_ctrl:1
	ds_write_b16 v146, v49 offset:64
	s_nop 0
	v_add_f32_dpp v34, v34, v34 quad_perm:[2,3,0,1] row_mask:0xf bank_mask:0xf bound_ctrl:1
	s_nop 1
	v_add_f32_dpp v34, v34, v34 row_half_mirror row_mask:0xf bank_mask:0xf bound_ctrl:1
	s_nop 1
	v_add_f32_dpp v34, v34, v34 row_mirror row_mask:0xf bank_mask:0xf bound_ctrl:1
	ds_bpermute_b32 v48, v118, v34
	s_and_saveexec_b64 s[8:9], s[4:5]
	s_cbranch_execz .LBB0_1303
	s_waitcnt lgkmcnt(0)
	v_add_f32_e32 v34, v34, v48
	v_lshl_add_u64 v[32:33], v[32:33], 2, s[94:95]
	global_atomic_add_f32 v[32:33], v34, off
.LBB0_1303:
	s_or_b64 exec, exec, s[8:9]
	v_or_b32_e32 v32, v135, v122
	v_add_u32_e32 v34, 0xffffc000, v32
	v_cmp_gt_i32_e32 vcc, s14, v32
	v_ashrrev_i32_e32 v33, 31, v32
	v_mov_b32_e32 v50, s41
	s_waitcnt lgkmcnt(0)
	v_cndmask_b32_e32 v48, v34, v32, vcc
	v_mov_b32_e32 v34, s43
	v_cndmask_b32_e32 v49, 0, v33, vcc
	v_cndmask_b32_e32 v95, v34, v50, vcc
	v_mov_b32_e32 v34, s42
	v_mov_b32_e32 v50, s40
	v_cndmask_b32_e32 v94, v34, v50, vcc
	v_lshlrev_b64 v[48:49], 12, v[48:49]
	v_lshl_add_u64 v[48:49], v[94:95], 0, v[48:49]
	v_lshl_add_u64 v[94:95], v[48:49], 0, v[64:65]
	v_accvgpr_read_b32 v34, a51
	v_lshlrev_b64 v[94:95], 12, v[32:33]
	v_lshl_add_u64 v[94:95], s[78:79], 0, v[94:95]
	v_lshl_add_u64 v[146:147], v[94:95], 0, v[64:65]
	v_lshl_add_u64 v[48:49], v[48:49], 0, v[92:93]
	v_add_f32_e32 v34, v51, v34
	global_store_dword v[146:147], v34, off
	v_accvgpr_read_b32 v50, a35
	v_subrev_u32_e32 v48, s6, v32
	v_mad_u64_u32 v[48:49], s[8:9], v48, s15, v[68:69]
	v_cvt_pk_bf16_f32 v51, v34, s0
	ds_write_b16 v48, v51
	v_add_f32_e32 v49, v35, v50
	v_mul_f32_e32 v35, v49, v49
	v_fmac_f32_e32 v35, v34, v34
	v_lshl_add_u64 v[50:51], v[94:95], 0, v[92:93]
	global_store_dword v[50:51], v49, off offset:128
	v_add_f32_dpp v34, v35, v35 quad_perm:[1,0,3,2] row_mask:0xf bank_mask:0xf bound_ctrl:1
	v_cvt_pk_bf16_f32 v49, v49, s0
	ds_write_b16 v48, v49 offset:64
	v_add_f32_dpp v34, v34, v34 quad_perm:[2,3,0,1] row_mask:0xf bank_mask:0xf bound_ctrl:1
	s_nop 1
	v_add_f32_dpp v34, v34, v34 row_half_mirror row_mask:0xf bank_mask:0xf bound_ctrl:1
	s_nop 1
	v_add_f32_dpp v34, v34, v34 row_mirror row_mask:0xf bank_mask:0xf bound_ctrl:1
	ds_bpermute_b32 v35, v118, v34
	s_and_saveexec_b64 s[8:9], s[4:5]
	s_cbranch_execz .LBB0_1305
	s_waitcnt lgkmcnt(0)
	v_add_f32_e32 v34, v34, v35
	v_lshl_add_u64 v[32:33], v[32:33], 2, s[94:95]
	global_atomic_add_f32 v[32:33], v34, off
.LBB0_1305:
	s_or_b64 exec, exec, s[8:9]
	v_or_b32_e32 v32, v135, v123
	v_add_u32_e32 v34, 0xffffc000, v32
	v_ashrrev_i32_e32 v33, 31, v32
	v_cmp_gt_i32_e32 vcc, s14, v32
	v_mov_b32_e32 v48, s43
	v_mov_b32_e32 v49, s41
	s_waitcnt lgkmcnt(0)
	v_cndmask_b32_e32 v35, 0, v33, vcc
	v_cndmask_b32_e32 v34, v34, v32, vcc
	v_cndmask_b32_e32 v49, v48, v49, vcc
	v_mov_b32_e32 v48, s42
	v_mov_b32_e32 v50, s40
	v_cndmask_b32_e32 v48, v48, v50, vcc
	v_lshlrev_b64 v[34:35], 12, v[34:35]
	v_lshl_add_u64 v[34:35], v[48:49], 0, v[34:35]
	v_lshl_add_u64 v[48:49], v[34:35], 0, v[64:65]
	v_accvgpr_read_b32 v94, a52
	v_lshlrev_b64 v[48:49], 12, v[32:33]
	v_lshl_add_u64 v[48:49], s[78:79], 0, v[48:49]
	v_mov_b32_e32 v93, v65
	v_lshl_add_u64 v[50:51], v[48:49], 0, v[64:65]
	v_lshl_add_u64 v[34:35], v[34:35], 0, v[92:93]
	v_lshl_add_u64 v[48:49], v[48:49], 0, v[92:93]
	v_add_f32_e32 v52, v52, v94
	global_store_dword v[50:51], v52, off
	v_accvgpr_read_b32 v34, a36
	v_subrev_u32_e32 v35, s6, v32
	v_mad_u64_u32 v[50:51], s[8:9], v35, s15, v[68:69]
	v_cvt_pk_bf16_f32 v94, v52, s0
	ds_write_b16 v50, v94
	v_add_f32_e32 v36, v36, v34
	v_mul_f32_e32 v34, v36, v36
	v_fmac_f32_e32 v34, v52, v52
	global_store_dword v[48:49], v36, off offset:128
	v_cvt_pk_bf16_f32 v36, v36, s0
	v_add_f32_dpp v34, v34, v34 quad_perm:[1,0,3,2] row_mask:0xf bank_mask:0xf bound_ctrl:1
	ds_write_b16 v50, v36 offset:64
	s_nop 0
	v_add_f32_dpp v34, v34, v34 quad_perm:[2,3,0,1] row_mask:0xf bank_mask:0xf bound_ctrl:1
	s_nop 1
	v_add_f32_dpp v34, v34, v34 row_half_mirror row_mask:0xf bank_mask:0xf bound_ctrl:1
	s_nop 1
	v_add_f32_dpp v34, v34, v34 row_mirror row_mask:0xf bank_mask:0xf bound_ctrl:1
	ds_bpermute_b32 v35, v118, v34
	s_and_saveexec_b64 s[8:9], s[4:5]
	s_cbranch_execz .LBB0_1307
	s_waitcnt lgkmcnt(0)
	v_add_f32_e32 v34, v34, v35
	v_lshl_add_u64 v[32:33], v[32:33], 2, s[94:95]
	global_atomic_add_f32 v[32:33], v34, off
; __device__ __forceinline__ u16 f2bf(float f) { return (u16)(pack2(f, f) & 0xffffu); }
; __device__ __forceinline__ float sum32(float v) { v = dpp_row_sum16(v); v += __shfl_xor(v, 16); return v; }
; __device__ __forceinline__ int rowmap(int e, int lane) { return (e & 3) + 8 * (e >> 2) + 4 * (lane >> 5); }
; __device__ __forceinline__ void phase4b(const Params& p, char* smem) {
;     ...
; #pragma unroll
;     for (int i = 0; i < 2; i++)
; #pragma unroll
;       for (int e = 0; e < 16; e++) {
;         const int row = m0 + wm * 64 + i * 32 + rowmap(e, lane);
;         const float* xr = xrow(p, row);
;         float sq = 0.f;
; #pragma unroll
;         for (int j = 0; j < 2; j++) {
;           const int col = n0 + wn * 64 + j * 32 + (lane & 31);
;           float v = acc[i][j][e] + xr[col];
;           X1[(size_t)row * 1024 + col] = v;
;           ((u16*)smem)[(row - m0) * 136 + (col - n0)] = f2bf(v);
;           sq += v * v;
;         }
;         sq = sum32(sq);
;         if ((lane & 31) == 0) atomicAdd(&SSQ1[row], sq);
;       }
.LBB0_1307:
	s_or_b64 exec, exec, s[8:9]
	v_or_b32_e32 v32, v135, v124
	v_add_u32_e32 v34, 0xffffc000, v32
	v_ashrrev_i32_e32 v33, 31, v32
	v_cmp_gt_i32_e32 vcc, s14, v32
	v_mov_b32_e32 v36, s43
	v_mov_b32_e32 v48, s41
	s_waitcnt lgkmcnt(0)
	v_cndmask_b32_e32 v35, 0, v33, vcc
	v_cndmask_b32_e32 v34, v34, v32, vcc
	v_cndmask_b32_e32 v49, v36, v48, vcc
	v_mov_b32_e32 v36, s42
	v_mov_b32_e32 v48, s40
	v_cndmask_b32_e32 v48, v36, v48, vcc
	v_lshlrev_b64 v[34:35], 12, v[34:35]
	v_lshl_add_u64 v[34:35], v[48:49], 0, v[34:35]
	v_lshl_add_u64 v[48:49], v[34:35], 0, v[64:65]
	v_accvgpr_read_b32 v36, a53
	v_lshlrev_b64 v[48:49], 12, v[32:33]
	v_lshl_add_u64 v[48:49], s[78:79], 0, v[48:49]
	v_lshl_add_u64 v[50:51], v[48:49], 0, v[64:65]
	v_lshl_add_u64 v[34:35], v[34:35], 0, v[92:93]
	v_add_f32_e32 v36, v53, v36
	global_store_dword v[50:51], v36, off
	v_accvgpr_read_b32 v34, a37
	v_subrev_u32_e32 v35, s6, v32
	v_mad_u64_u32 v[50:51], s[8:9], v35, s15, v[68:69]
	v_cvt_pk_bf16_f32 v52, v36, s0
	ds_write_b16 v50, v52
	v_add_f32_e32 v51, v37, v34
	v_mul_f32_e32 v34, v51, v51
	v_fmac_f32_e32 v34, v36, v36
	v_lshl_add_u64 v[36:37], v[48:49], 0, v[92:93]
	global_store_dword v[36:37], v51, off offset:128
	v_add_f32_dpp v34, v34, v34 quad_perm:[1,0,3,2] row_mask:0xf bank_mask:0xf bound_ctrl:1
	v_cvt_pk_bf16_f32 v36, v51, s0
	ds_write_b16 v50, v36 offset:64
	v_add_f32_dpp v34, v34, v34 quad_perm:[2,3,0,1] row_mask:0xf bank_mask:0xf bound_ctrl:1
	s_nop 1
	v_add_f32_dpp v34, v34, v34 row_half_mirror row_mask:0xf bank_mask:0xf bound_ctrl:1
	s_nop 1
	v_add_f32_dpp v34, v34, v34 row_mirror row_mask:0xf bank_mask:0xf bound_ctrl:1
	ds_bpermute_b32 v35, v118, v34
	s_and_saveexec_b64 s[8:9], s[4:5]
	s_cbranch_execz .LBB0_1309
	s_waitcnt lgkmcnt(0)
	v_add_f32_e32 v34, v34, v35
	v_lshl_add_u64 v[32:33], v[32:33], 2, s[94:95]
	global_atomic_add_f32 v[32:33], v34, off
.LBB0_1309:
	s_or_b64 exec, exec, s[8:9]
	v_or_b32_e32 v32, v135, v125
	v_add_u32_e32 v34, 0xffffc000, v32
	v_ashrrev_i32_e32 v33, 31, v32
	v_cmp_gt_i32_e32 vcc, s14, v32
	v_mov_b32_e32 v36, s43
	v_mov_b32_e32 v37, s41
	s_waitcnt lgkmcnt(0)
	v_cndmask_b32_e32 v35, 0, v33, vcc
	v_cndmask_b32_e32 v34, v34, v32, vcc
	v_cndmask_b32_e32 v37, v36, v37, vcc
	v_mov_b32_e32 v36, s42
	v_mov_b32_e32 v48, s40
	v_cndmask_b32_e32 v36, v36, v48, vcc
	v_lshlrev_b64 v[34:35], 12, v[34:35]
	v_lshl_add_u64 v[34:35], v[36:37], 0, v[34:35]
	v_lshl_add_u64 v[36:37], v[34:35], 0, v[64:65]
	v_accvgpr_read_b32 v50, a54
	v_lshlrev_b64 v[36:37], 12, v[32:33]
	v_lshl_add_u64 v[36:37], s[78:79], 0, v[36:37]
	v_mov_b32_e32 v93, v65
	v_lshl_add_u64 v[48:49], v[36:37], 0, v[64:65]
	v_lshl_add_u64 v[34:35], v[34:35], 0, v[92:93]
	v_lshl_add_u64 v[36:37], v[36:37], 0, v[92:93]
	v_add_f32_e32 v50, v54, v50
	global_store_dword v[48:49], v50, off
	v_accvgpr_read_b32 v34, a38
	v_subrev_u32_e32 v35, s6, v32
	v_mad_u64_u32 v[48:49], s[8:9], v35, s15, v[68:69]
	v_cvt_pk_bf16_f32 v51, v50, s0
	ds_write_b16 v48, v51
	v_add_f32_e32 v38, v38, v34
	v_mul_f32_e32 v34, v38, v38
	v_fmac_f32_e32 v34, v50, v50
	global_store_dword v[36:37], v38, off offset:128
	v_cvt_pk_bf16_f32 v36, v38, s0
	v_add_f32_dpp v34, v34, v34 quad_perm:[1,0,3,2] row_mask:0xf bank_mask:0xf bound_ctrl:1
	ds_write_b16 v48, v36 offset:64
	s_nop 0
	v_add_f32_dpp v34, v34, v34 quad_perm:[2,3,0,1] row_mask:0xf bank_mask:0xf bound_ctrl:1
	s_nop 1
	v_add_f32_dpp v34, v34, v34 row_half_mirror row_mask:0xf bank_mask:0xf bound_ctrl:1
	s_nop 1
	v_add_f32_dpp v34, v34, v34 row_mirror row_mask:0xf bank_mask:0xf bound_ctrl:1
	ds_bpermute_b32 v35, v118, v34
	s_and_saveexec_b64 s[8:9], s[4:5]
	s_cbranch_execz .LBB0_1311
	s_waitcnt lgkmcnt(0)
	v_add_f32_e32 v34, v34, v35
	v_lshl_add_u64 v[32:33], v[32:33], 2, s[94:95]
	global_atomic_add_f32 v[32:33], v34, off
.LBB0_1311:
	s_or_b64 exec, exec, s[8:9]
	v_or_b32_e32 v32, v135, v126
	v_add_u32_e32 v34, 0xffffc000, v32
	v_ashrrev_i32_e32 v33, 31, v32
	v_cmp_gt_i32_e32 vcc, s14, v32
	v_mov_b32_e32 v36, s43
	v_mov_b32_e32 v37, s41
	s_waitcnt lgkmcnt(0)
	v_cndmask_b32_e32 v35, 0, v33, vcc
	v_cndmask_b32_e32 v34, v34, v32, vcc
	v_cndmask_b32_e32 v37, v36, v37, vcc
	v_mov_b32_e32 v36, s42
	v_mov_b32_e32 v38, s40
	v_cndmask_b32_e32 v36, v36, v38, vcc
	v_lshlrev_b64 v[34:35], 12, v[34:35]
	v_lshl_add_u64 v[34:35], v[36:37], 0, v[34:35]
	v_lshl_add_u64 v[36:37], v[34:35], 0, v[64:65]
	v_accvgpr_read_b32 v38, a55
	v_lshlrev_b64 v[36:37], 12, v[32:33]
	v_lshl_add_u64 v[36:37], s[78:79], 0, v[36:37]
	v_lshl_add_u64 v[48:49], v[36:37], 0, v[64:65]
	v_lshl_add_u64 v[34:35], v[34:35], 0, v[92:93]
	v_lshl_add_u64 v[36:37], v[36:37], 0, v[92:93]
	v_add_f32_e32 v38, v55, v38
	global_store_dword v[48:49], v38, off
	v_accvgpr_read_b32 v34, a39
	v_subrev_u32_e32 v35, s6, v32
	v_mad_u64_u32 v[48:49], s[8:9], v35, s15, v[68:69]
	v_cvt_pk_bf16_f32 v50, v38, s0
	ds_write_b16 v48, v50
	v_add_f32_e32 v39, v39, v34
	v_mul_f32_e32 v34, v39, v39
	v_fmac_f32_e32 v34, v38, v38
	global_store_dword v[36:37], v39, off offset:128
	v_cvt_pk_bf16_f32 v36, v39, s0
	v_add_f32_dpp v34, v34, v34 quad_perm:[1,0,3,2] row_mask:0xf bank_mask:0xf bound_ctrl:1
	ds_write_b16 v48, v36 offset:64
	s_nop 0
	v_add_f32_dpp v34, v34, v34 quad_perm:[2,3,0,1] row_mask:0xf bank_mask:0xf bound_ctrl:1
	s_nop 1
	v_add_f32_dpp v34, v34, v34 row_half_mirror row_mask:0xf bank_mask:0xf bound_ctrl:1
	s_nop 1
	v_add_f32_dpp v34, v34, v34 row_mirror row_mask:0xf bank_mask:0xf bound_ctrl:1
	ds_bpermute_b32 v35, v118, v34
	s_and_saveexec_b64 s[8:9], s[4:5]
	s_cbranch_execz .LBB0_1313
	s_waitcnt lgkmcnt(0)
	v_add_f32_e32 v34, v34, v35
	v_lshl_add_u64 v[32:33], v[32:33], 2, s[94:95]
	global_atomic_add_f32 v[32:33], v34, off
; __device__ __forceinline__ u16 f2bf(float f) { return (u16)(pack2(f, f) & 0xffffu); }
; __device__ __forceinline__ float sum32(float v) { v = dpp_row_sum16(v); v += __shfl_xor(v, 16); return v; }
; __device__ __forceinline__ int rowmap(int e, int lane) { return (e & 3) + 8 * (e >> 2) + 4 * (lane >> 5); }
; __device__ __forceinline__ void phase4b(const Params& p, char* smem) {
;     ...
; #pragma unroll
;     for (int i = 0; i < 2; i++)
; #pragma unroll
;       for (int e = 0; e < 16; e++) {
;         const int row = m0 + wm * 64 + i * 32 + rowmap(e, lane);
;         const float* xr = xrow(p, row);
;         float sq = 0.f;
; #pragma unroll
;         for (int j = 0; j < 2; j++) {
;           const int col = n0 + wn * 64 + j * 32 + (lane & 31);
;           float v = acc[i][j][e] + xr[col];
;           X1[(size_t)row * 1024 + col] = v;
;           ((u16*)smem)[(row - m0) * 136 + (col - n0)] = f2bf(v);
;           sq += v * v;
;         }
;         sq = sum32(sq);
;         if ((lane & 31) == 0) atomicAdd(&SSQ1[row], sq);
;       }
.LBB0_1313:
	s_or_b64 exec, exec, s[8:9]
	v_or_b32_e32 v32, v135, v127
	v_add_u32_e32 v34, 0xffffc000, v32
	v_ashrrev_i32_e32 v33, 31, v32
	v_cmp_gt_i32_e32 vcc, s14, v32
	v_mov_b32_e32 v36, s43
	v_mov_b32_e32 v37, s41
	s_waitcnt lgkmcnt(0)
	v_cndmask_b32_e32 v35, 0, v33, vcc
	v_cndmask_b32_e32 v34, v34, v32, vcc
	v_cndmask_b32_e32 v37, v36, v37, vcc
	v_mov_b32_e32 v36, s42
	v_mov_b32_e32 v38, s40
	v_cndmask_b32_e32 v36, v36, v38, vcc
	v_lshlrev_b64 v[34:35], 12, v[34:35]
	v_lshl_add_u64 v[34:35], v[36:37], 0, v[34:35]
	v_lshl_add_u64 v[36:37], v[34:35], 0, v[64:65]
	v_accvgpr_read_b32 v48, a56
	v_lshlrev_b64 v[36:37], 12, v[32:33]
	v_lshl_add_u64 v[36:37], s[78:79], 0, v[36:37]
	v_mov_b32_e32 v93, v65
	v_lshl_add_u64 v[38:39], v[36:37], 0, v[64:65]
	v_lshl_add_u64 v[34:35], v[34:35], 0, v[92:93]
	v_lshl_add_u64 v[36:37], v[36:37], 0, v[92:93]
	v_add_f32_e32 v48, v56, v48
	global_store_dword v[38:39], v48, off
	v_accvgpr_read_b32 v34, a40
	v_subrev_u32_e32 v35, s6, v32
	v_mad_u64_u32 v[38:39], s[8:9], v35, s15, v[68:69]
	v_cvt_pk_bf16_f32 v49, v48, s0
	ds_write_b16 v38, v49
	v_add_f32_e32 v39, v40, v34
	v_mul_f32_e32 v34, v39, v39
	v_fmac_f32_e32 v34, v48, v48
	global_store_dword v[36:37], v39, off offset:128
	v_cvt_pk_bf16_f32 v36, v39, s0
	v_add_f32_dpp v34, v34, v34 quad_perm:[1,0,3,2] row_mask:0xf bank_mask:0xf bound_ctrl:1
	ds_write_b16 v38, v36 offset:64
	s_nop 0
	v_add_f32_dpp v34, v34, v34 quad_perm:[2,3,0,1] row_mask:0xf bank_mask:0xf bound_ctrl:1
	s_nop 1
	v_add_f32_dpp v34, v34, v34 row_half_mirror row_mask:0xf bank_mask:0xf bound_ctrl:1
	s_nop 1
	v_add_f32_dpp v34, v34, v34 row_mirror row_mask:0xf bank_mask:0xf bound_ctrl:1
	ds_bpermute_b32 v35, v118, v34
	s_and_saveexec_b64 s[8:9], s[4:5]
	s_cbranch_execz .LBB0_1315
	s_waitcnt lgkmcnt(0)
	v_add_f32_e32 v34, v34, v35
	v_lshl_add_u64 v[32:33], v[32:33], 2, s[94:95]
	global_atomic_add_f32 v[32:33], v34, off
.LBB0_1315:
	s_or_b64 exec, exec, s[8:9]
	v_or_b32_e32 v32, v135, v128
	v_add_u32_e32 v34, 0xffffc000, v32
	v_ashrrev_i32_e32 v33, 31, v32
	v_cmp_gt_i32_e32 vcc, s14, v32
	v_mov_b32_e32 v36, s43
	v_mov_b32_e32 v37, s41
	s_waitcnt lgkmcnt(0)
	v_cndmask_b32_e32 v35, 0, v33, vcc
	v_cndmask_b32_e32 v34, v34, v32, vcc
	v_cndmask_b32_e32 v37, v36, v37, vcc
	v_mov_b32_e32 v36, s42
	v_mov_b32_e32 v38, s40
	v_cndmask_b32_e32 v36, v36, v38, vcc
	v_lshlrev_b64 v[34:35], 12, v[34:35]
	v_lshl_add_u64 v[34:35], v[36:37], 0, v[34:35]
	v_lshl_add_u64 v[36:37], v[34:35], 0, v[64:65]
	v_accvgpr_read_b32 v40, a57
	v_lshlrev_b64 v[36:37], 12, v[32:33]
	v_lshl_add_u64 v[36:37], s[78:79], 0, v[36:37]
	v_lshl_add_u64 v[38:39], v[36:37], 0, v[64:65]
	v_lshl_add_u64 v[34:35], v[34:35], 0, v[92:93]
	v_lshl_add_u64 v[36:37], v[36:37], 0, v[92:93]
	v_add_f32_e32 v40, v57, v40
	global_store_dword v[38:39], v40, off
	v_accvgpr_read_b32 v34, a41
	v_subrev_u32_e32 v35, s6, v32
	v_mad_u64_u32 v[38:39], s[8:9], v35, s15, v[68:69]
	v_cvt_pk_bf16_f32 v48, v40, s0
	ds_write_b16 v38, v48
	v_add_f32_e32 v39, v41, v34
	v_mul_f32_e32 v34, v39, v39
	v_fmac_f32_e32 v34, v40, v40
	global_store_dword v[36:37], v39, off offset:128
	v_cvt_pk_bf16_f32 v36, v39, s0
	v_add_f32_dpp v34, v34, v34 quad_perm:[1,0,3,2] row_mask:0xf bank_mask:0xf bound_ctrl:1
	ds_write_b16 v38, v36 offset:64
	s_nop 0
	v_add_f32_dpp v34, v34, v34 quad_perm:[2,3,0,1] row_mask:0xf bank_mask:0xf bound_ctrl:1
	s_nop 1
	v_add_f32_dpp v34, v34, v34 row_half_mirror row_mask:0xf bank_mask:0xf bound_ctrl:1
	s_nop 1
	v_add_f32_dpp v34, v34, v34 row_mirror row_mask:0xf bank_mask:0xf bound_ctrl:1
	ds_bpermute_b32 v35, v118, v34
	s_and_saveexec_b64 s[8:9], s[4:5]
	s_cbranch_execz .LBB0_1317
	s_waitcnt lgkmcnt(0)
	v_add_f32_e32 v34, v34, v35
	v_lshl_add_u64 v[32:33], v[32:33], 2, s[94:95]
	global_atomic_add_f32 v[32:33], v34, off
.LBB0_1317:
	s_or_b64 exec, exec, s[8:9]
	v_or_b32_e32 v32, v135, v129
	v_add_u32_e32 v34, 0xffffc000, v32
	v_ashrrev_i32_e32 v33, 31, v32
	v_cmp_gt_i32_e32 vcc, s14, v32
	v_mov_b32_e32 v36, s43
	v_mov_b32_e32 v37, s41
	s_waitcnt lgkmcnt(0)
	v_cndmask_b32_e32 v35, 0, v33, vcc
	v_cndmask_b32_e32 v34, v34, v32, vcc
	v_cndmask_b32_e32 v37, v36, v37, vcc
	v_mov_b32_e32 v36, s42
	v_mov_b32_e32 v38, s40
	v_cndmask_b32_e32 v36, v36, v38, vcc
	v_lshlrev_b64 v[34:35], 12, v[34:35]
	v_lshl_add_u64 v[34:35], v[36:37], 0, v[34:35]
	v_lshl_add_u64 v[36:37], v[34:35], 0, v[64:65]
	v_accvgpr_read_b32 v40, a58
	v_lshlrev_b64 v[36:37], 12, v[32:33]
	v_lshl_add_u64 v[36:37], s[78:79], 0, v[36:37]
	v_mov_b32_e32 v93, v65
	v_lshl_add_u64 v[38:39], v[36:37], 0, v[64:65]
	v_lshl_add_u64 v[34:35], v[34:35], 0, v[92:93]
	v_lshl_add_u64 v[36:37], v[36:37], 0, v[92:93]
	v_add_f32_e32 v40, v58, v40
	global_store_dword v[38:39], v40, off
	v_accvgpr_read_b32 v34, a42
	v_subrev_u32_e32 v35, s6, v32
	v_mad_u64_u32 v[38:39], s[8:9], v35, s15, v[68:69]
	v_cvt_pk_bf16_f32 v41, v40, s0
	ds_write_b16 v38, v41
	v_add_f32_e32 v39, v42, v34
	v_mul_f32_e32 v34, v39, v39
	v_fmac_f32_e32 v34, v40, v40
	global_store_dword v[36:37], v39, off offset:128
	v_cvt_pk_bf16_f32 v36, v39, s0
	v_add_f32_dpp v34, v34, v34 quad_perm:[1,0,3,2] row_mask:0xf bank_mask:0xf bound_ctrl:1
	ds_write_b16 v38, v36 offset:64
	s_nop 0
	v_add_f32_dpp v34, v34, v34 quad_perm:[2,3,0,1] row_mask:0xf bank_mask:0xf bound_ctrl:1
	s_nop 1
	v_add_f32_dpp v34, v34, v34 row_half_mirror row_mask:0xf bank_mask:0xf bound_ctrl:1
	s_nop 1
	v_add_f32_dpp v34, v34, v34 row_mirror row_mask:0xf bank_mask:0xf bound_ctrl:1
	ds_bpermute_b32 v35, v118, v34
	s_and_saveexec_b64 s[8:9], s[4:5]
	s_cbranch_execz .LBB0_1319
	s_waitcnt lgkmcnt(0)
	v_add_f32_e32 v34, v34, v35
	v_lshl_add_u64 v[32:33], v[32:33], 2, s[94:95]
	global_atomic_add_f32 v[32:33], v34, off
; __device__ __forceinline__ u16 f2bf(float f) { return (u16)(pack2(f, f) & 0xffffu); }
; __device__ __forceinline__ float sum32(float v) { v = dpp_row_sum16(v); v += __shfl_xor(v, 16); return v; }
; __device__ __forceinline__ int rowmap(int e, int lane) { return (e & 3) + 8 * (e >> 2) + 4 * (lane >> 5); }
; __device__ __forceinline__ void phase4b(const Params& p, char* smem) {
;     ...
; #pragma unroll
;     for (int i = 0; i < 2; i++)
; #pragma unroll
;       for (int e = 0; e < 16; e++) {
;         const int row = m0 + wm * 64 + i * 32 + rowmap(e, lane);
;         const float* xr = xrow(p, row);
;         float sq = 0.f;
; #pragma unroll
;         for (int j = 0; j < 2; j++) {
;           const int col = n0 + wn * 64 + j * 32 + (lane & 31);
;           float v = acc[i][j][e] + xr[col];
;           X1[(size_t)row * 1024 + col] = v;
;           ((u16*)smem)[(row - m0) * 136 + (col - n0)] = f2bf(v);
;           sq += v * v;
;         }
;         sq = sum32(sq);
;         if ((lane & 31) == 0) atomicAdd(&SSQ1[row], sq);
;       }
.LBB0_1319:
	s_or_b64 exec, exec, s[8:9]
	v_or_b32_e32 v32, v135, v130
	v_add_u32_e32 v34, 0xffffc000, v32
	v_ashrrev_i32_e32 v33, 31, v32
	v_cmp_gt_i32_e32 vcc, s14, v32
	v_mov_b32_e32 v36, s43
	v_mov_b32_e32 v37, s41
	s_waitcnt lgkmcnt(0)
	v_cndmask_b32_e32 v35, 0, v33, vcc
	v_cndmask_b32_e32 v34, v34, v32, vcc
	v_cndmask_b32_e32 v37, v36, v37, vcc
	v_mov_b32_e32 v36, s42
	v_mov_b32_e32 v38, s40
	v_cndmask_b32_e32 v36, v36, v38, vcc
	v_lshlrev_b64 v[34:35], 12, v[34:35]
	v_lshl_add_u64 v[34:35], v[36:37], 0, v[34:35]
	v_lshl_add_u64 v[36:37], v[34:35], 0, v[64:65]
	v_accvgpr_read_b32 v40, a59
	v_lshlrev_b64 v[36:37], 12, v[32:33]
	v_lshl_add_u64 v[36:37], s[78:79], 0, v[36:37]
	v_lshl_add_u64 v[38:39], v[36:37], 0, v[64:65]
	v_lshl_add_u64 v[34:35], v[34:35], 0, v[92:93]
	v_lshl_add_u64 v[36:37], v[36:37], 0, v[92:93]
	v_add_f32_e32 v40, v59, v40
	global_store_dword v[38:39], v40, off
	v_accvgpr_read_b32 v34, a43
	v_subrev_u32_e32 v35, s6, v32
	v_mad_u64_u32 v[38:39], s[8:9], v35, s15, v[68:69]
	v_cvt_pk_bf16_f32 v41, v40, s0
	ds_write_b16 v38, v41
	v_add_f32_e32 v39, v43, v34
	v_mul_f32_e32 v34, v39, v39
	v_fmac_f32_e32 v34, v40, v40
	global_store_dword v[36:37], v39, off offset:128
	v_cvt_pk_bf16_f32 v36, v39, s0
	v_add_f32_dpp v34, v34, v34 quad_perm:[1,0,3,2] row_mask:0xf bank_mask:0xf bound_ctrl:1
	ds_write_b16 v38, v36 offset:64
	s_nop 0
	v_add_f32_dpp v34, v34, v34 quad_perm:[2,3,0,1] row_mask:0xf bank_mask:0xf bound_ctrl:1
	s_nop 1
	v_add_f32_dpp v34, v34, v34 row_half_mirror row_mask:0xf bank_mask:0xf bound_ctrl:1
	s_nop 1
	v_add_f32_dpp v34, v34, v34 row_mirror row_mask:0xf bank_mask:0xf bound_ctrl:1
	ds_bpermute_b32 v35, v118, v34
	s_and_saveexec_b64 s[8:9], s[4:5]
	s_cbranch_execz .LBB0_1321
	s_waitcnt lgkmcnt(0)
	v_add_f32_e32 v34, v34, v35
	v_lshl_add_u64 v[32:33], v[32:33], 2, s[94:95]
	global_atomic_add_f32 v[32:33], v34, off
.LBB0_1321:
	s_or_b64 exec, exec, s[8:9]
	v_or_b32_e32 v32, v135, v131
	v_add_u32_e32 v34, 0xffffc000, v32
	v_ashrrev_i32_e32 v33, 31, v32
	v_cmp_gt_i32_e32 vcc, s14, v32
	v_mov_b32_e32 v36, s43
	v_mov_b32_e32 v37, s41
	s_waitcnt lgkmcnt(0)
	v_cndmask_b32_e32 v35, 0, v33, vcc
	v_cndmask_b32_e32 v34, v34, v32, vcc
	v_cndmask_b32_e32 v37, v36, v37, vcc
	v_mov_b32_e32 v36, s42
	v_mov_b32_e32 v38, s40
	v_cndmask_b32_e32 v36, v36, v38, vcc
	v_lshlrev_b64 v[34:35], 12, v[34:35]
	v_lshl_add_u64 v[34:35], v[36:37], 0, v[34:35]
	v_lshl_add_u64 v[36:37], v[34:35], 0, v[64:65]
	v_accvgpr_read_b32 v40, a60
	v_lshlrev_b64 v[36:37], 12, v[32:33]
	v_lshl_add_u64 v[36:37], s[78:79], 0, v[36:37]
	v_mov_b32_e32 v93, v65
	v_lshl_add_u64 v[38:39], v[36:37], 0, v[64:65]
	v_lshl_add_u64 v[34:35], v[34:35], 0, v[92:93]
	v_lshl_add_u64 v[36:37], v[36:37], 0, v[92:93]
	v_add_f32_e32 v40, v60, v40
	global_store_dword v[38:39], v40, off
	v_accvgpr_read_b32 v34, a44
	v_subrev_u32_e32 v35, s6, v32
	v_mad_u64_u32 v[38:39], s[8:9], v35, s15, v[68:69]
	v_cvt_pk_bf16_f32 v41, v40, s0
	ds_write_b16 v38, v41
	v_add_f32_e32 v39, v44, v34
	v_mul_f32_e32 v34, v39, v39
	v_fmac_f32_e32 v34, v40, v40
	global_store_dword v[36:37], v39, off offset:128
	v_cvt_pk_bf16_f32 v36, v39, s0
	v_add_f32_dpp v34, v34, v34 quad_perm:[1,0,3,2] row_mask:0xf bank_mask:0xf bound_ctrl:1
	ds_write_b16 v38, v36 offset:64
	s_nop 0
	v_add_f32_dpp v34, v34, v34 quad_perm:[2,3,0,1] row_mask:0xf bank_mask:0xf bound_ctrl:1
	s_nop 1
	v_add_f32_dpp v34, v34, v34 row_half_mirror row_mask:0xf bank_mask:0xf bound_ctrl:1
	s_nop 1
	v_add_f32_dpp v34, v34, v34 row_mirror row_mask:0xf bank_mask:0xf bound_ctrl:1
	ds_bpermute_b32 v35, v118, v34
	s_and_saveexec_b64 s[8:9], s[4:5]
	s_cbranch_execz .LBB0_1323
	s_waitcnt lgkmcnt(0)
	v_add_f32_e32 v34, v34, v35
	v_lshl_add_u64 v[32:33], v[32:33], 2, s[94:95]
	global_atomic_add_f32 v[32:33], v34, off
.LBB0_1323:
	s_or_b64 exec, exec, s[8:9]
	v_or_b32_e32 v32, v135, v132
	v_add_u32_e32 v34, 0xffffc000, v32
	v_ashrrev_i32_e32 v33, 31, v32
	v_cmp_gt_i32_e32 vcc, s14, v32
	v_mov_b32_e32 v36, s43
	v_mov_b32_e32 v37, s41
	s_waitcnt lgkmcnt(0)
	v_cndmask_b32_e32 v35, 0, v33, vcc
	v_cndmask_b32_e32 v34, v34, v32, vcc
	v_cndmask_b32_e32 v37, v36, v37, vcc
	v_mov_b32_e32 v36, s42
	v_mov_b32_e32 v38, s40
	v_cndmask_b32_e32 v36, v36, v38, vcc
	v_lshlrev_b64 v[34:35], 12, v[34:35]
	v_lshl_add_u64 v[34:35], v[36:37], 0, v[34:35]
	v_lshl_add_u64 v[36:37], v[34:35], 0, v[64:65]
	v_accvgpr_read_b32 v40, a61
	v_lshlrev_b64 v[36:37], 12, v[32:33]
	v_lshl_add_u64 v[36:37], s[78:79], 0, v[36:37]
	v_lshl_add_u64 v[38:39], v[36:37], 0, v[64:65]
	v_lshl_add_u64 v[34:35], v[34:35], 0, v[92:93]
	v_lshl_add_u64 v[36:37], v[36:37], 0, v[92:93]
	v_add_f32_e32 v40, v61, v40
	global_store_dword v[38:39], v40, off
	v_accvgpr_read_b32 v34, a45
	v_subrev_u32_e32 v35, s6, v32
	v_mad_u64_u32 v[38:39], s[8:9], v35, s15, v[68:69]
	v_cvt_pk_bf16_f32 v41, v40, s0
	ds_write_b16 v38, v41
	v_add_f32_e32 v39, v45, v34
	v_mul_f32_e32 v34, v39, v39
	v_fmac_f32_e32 v34, v40, v40
	global_store_dword v[36:37], v39, off offset:128
	v_cvt_pk_bf16_f32 v36, v39, s0
	v_add_f32_dpp v34, v34, v34 quad_perm:[1,0,3,2] row_mask:0xf bank_mask:0xf bound_ctrl:1
	ds_write_b16 v38, v36 offset:64
	s_nop 0
	v_add_f32_dpp v34, v34, v34 quad_perm:[2,3,0,1] row_mask:0xf bank_mask:0xf bound_ctrl:1
	s_nop 1
	v_add_f32_dpp v34, v34, v34 row_half_mirror row_mask:0xf bank_mask:0xf bound_ctrl:1
	s_nop 1
	v_add_f32_dpp v34, v34, v34 row_mirror row_mask:0xf bank_mask:0xf bound_ctrl:1
	ds_bpermute_b32 v35, v118, v34
	s_and_saveexec_b64 s[8:9], s[4:5]
	s_cbranch_execz .LBB0_1325
	s_waitcnt lgkmcnt(0)
	v_add_f32_e32 v34, v34, v35
	v_lshl_add_u64 v[32:33], v[32:33], 2, s[94:95]
	global_atomic_add_f32 v[32:33], v34, off
; __device__ __forceinline__ u16 f2bf(float f) { return (u16)(pack2(f, f) & 0xffffu); }
; __device__ __forceinline__ float sum32(float v) { v = dpp_row_sum16(v); v += __shfl_xor(v, 16); return v; }
; __device__ __forceinline__ int rowmap(int e, int lane) { return (e & 3) + 8 * (e >> 2) + 4 * (lane >> 5); }
; __device__ __forceinline__ void phase4b(const Params& p, char* smem) {
;     ...
; #pragma unroll
;     for (int i = 0; i < 2; i++)
; #pragma unroll
;       for (int e = 0; e < 16; e++) {
;         const int row = m0 + wm * 64 + i * 32 + rowmap(e, lane);
;         const float* xr = xrow(p, row);
;         float sq = 0.f;
; #pragma unroll
;         for (int j = 0; j < 2; j++) {
;           const int col = n0 + wn * 64 + j * 32 + (lane & 31);
;           float v = acc[i][j][e] + xr[col];
;           X1[(size_t)row * 1024 + col] = v;
;           ((u16*)smem)[(row - m0) * 136 + (col - n0)] = f2bf(v);
;           sq += v * v;
;         }
;         sq = sum32(sq);
;         if ((lane & 31) == 0) atomicAdd(&SSQ1[row], sq);
;       }
.LBB0_1325:
	s_or_b64 exec, exec, s[8:9]
	v_or_b32_e32 v32, v135, v133
	v_add_u32_e32 v34, 0xffffc000, v32
	v_ashrrev_i32_e32 v33, 31, v32
	v_cmp_gt_i32_e32 vcc, s14, v32
	v_mov_b32_e32 v36, s43
	v_mov_b32_e32 v37, s41
	s_waitcnt lgkmcnt(0)
	v_cndmask_b32_e32 v35, 0, v33, vcc
	v_cndmask_b32_e32 v34, v34, v32, vcc
	v_cndmask_b32_e32 v37, v36, v37, vcc
	v_mov_b32_e32 v36, s42
	v_mov_b32_e32 v38, s40
	v_cndmask_b32_e32 v36, v36, v38, vcc
	v_lshlrev_b64 v[34:35], 12, v[34:35]
	v_lshl_add_u64 v[34:35], v[36:37], 0, v[34:35]
	v_lshl_add_u64 v[36:37], v[34:35], 0, v[64:65]
	v_accvgpr_read_b32 v40, a62
	v_lshlrev_b64 v[36:37], 12, v[32:33]
	v_lshl_add_u64 v[36:37], s[78:79], 0, v[36:37]
	v_mov_b32_e32 v93, v65
	v_lshl_add_u64 v[38:39], v[36:37], 0, v[64:65]
	v_lshl_add_u64 v[34:35], v[34:35], 0, v[92:93]
	v_lshl_add_u64 v[36:37], v[36:37], 0, v[92:93]
	v_add_f32_e32 v40, v62, v40
	global_store_dword v[38:39], v40, off
	v_accvgpr_read_b32 v34, a46
	v_subrev_u32_e32 v35, s6, v32
	v_mad_u64_u32 v[38:39], s[8:9], v35, s15, v[68:69]
	v_cvt_pk_bf16_f32 v41, v40, s0
	ds_write_b16 v38, v41
	v_add_f32_e32 v39, v46, v34
	v_mul_f32_e32 v34, v39, v39
	v_fmac_f32_e32 v34, v40, v40
	global_store_dword v[36:37], v39, off offset:128
	v_cvt_pk_bf16_f32 v36, v39, s0
	v_add_f32_dpp v34, v34, v34 quad_perm:[1,0,3,2] row_mask:0xf bank_mask:0xf bound_ctrl:1
	ds_write_b16 v38, v36 offset:64
	s_nop 0
	v_add_f32_dpp v34, v34, v34 quad_perm:[2,3,0,1] row_mask:0xf bank_mask:0xf bound_ctrl:1
	s_nop 1
	v_add_f32_dpp v34, v34, v34 row_half_mirror row_mask:0xf bank_mask:0xf bound_ctrl:1
	s_nop 1
	v_add_f32_dpp v34, v34, v34 row_mirror row_mask:0xf bank_mask:0xf bound_ctrl:1
	ds_bpermute_b32 v35, v118, v34
	s_and_saveexec_b64 s[8:9], s[4:5]
	s_cbranch_execz .LBB0_1327
	s_waitcnt lgkmcnt(0)
	v_add_f32_e32 v34, v34, v35
	v_lshl_add_u64 v[32:33], v[32:33], 2, s[94:95]
	global_atomic_add_f32 v[32:33], v34, off
.LBB0_1327:
	s_or_b64 exec, exec, s[8:9]
	v_or_b32_e32 v32, v135, v134
	v_add_u32_e32 v34, 0xffffc000, v32
	v_ashrrev_i32_e32 v33, 31, v32
	v_cmp_gt_i32_e32 vcc, s14, v32
	v_mov_b32_e32 v36, s43
	v_mov_b32_e32 v37, s41
	s_waitcnt lgkmcnt(0)
	v_cndmask_b32_e32 v35, 0, v33, vcc
	v_cndmask_b32_e32 v34, v34, v32, vcc
	v_cndmask_b32_e32 v37, v36, v37, vcc
	v_mov_b32_e32 v36, s42
	v_mov_b32_e32 v38, s40
	v_cndmask_b32_e32 v36, v36, v38, vcc
	v_lshlrev_b64 v[34:35], 12, v[34:35]
	v_lshl_add_u64 v[34:35], v[36:37], 0, v[34:35]
	v_lshl_add_u64 v[36:37], v[34:35], 0, v[64:65]
	v_accvgpr_read_b32 v40, a63
	v_lshlrev_b64 v[36:37], 12, v[32:33]
	v_lshl_add_u64 v[36:37], s[78:79], 0, v[36:37]
	v_lshl_add_u64 v[38:39], v[36:37], 0, v[64:65]
	v_lshl_add_u64 v[34:35], v[34:35], 0, v[92:93]
	v_lshl_add_u64 v[36:37], v[36:37], 0, v[92:93]
	v_add_f32_e32 v40, v63, v40
	global_store_dword v[38:39], v40, off
	v_accvgpr_read_b32 v34, a47
	v_subrev_u32_e32 v35, s6, v32
	v_mad_u64_u32 v[38:39], s[8:9], v35, s15, v[68:69]
	v_cvt_pk_bf16_f32 v41, v40, s0
	ds_write_b16 v38, v41
	v_add_f32_e32 v39, v47, v34
	v_mul_f32_e32 v34, v39, v39
	v_fmac_f32_e32 v34, v40, v40
	global_store_dword v[36:37], v39, off offset:128
	v_cvt_pk_bf16_f32 v36, v39, s0
	v_add_f32_dpp v34, v34, v34 quad_perm:[1,0,3,2] row_mask:0xf bank_mask:0xf bound_ctrl:1
	ds_write_b16 v38, v36 offset:64
	s_nop 0
	v_add_f32_dpp v34, v34, v34 quad_perm:[2,3,0,1] row_mask:0xf bank_mask:0xf bound_ctrl:1
	s_nop 1
	v_add_f32_dpp v34, v34, v34 row_half_mirror row_mask:0xf bank_mask:0xf bound_ctrl:1
	s_nop 1
	v_add_f32_dpp v34, v34, v34 row_mirror row_mask:0xf bank_mask:0xf bound_ctrl:1
	ds_bpermute_b32 v35, v118, v34
	s_and_saveexec_b64 s[8:9], s[4:5]
	s_cbranch_execz .LBB0_1329
	s_waitcnt lgkmcnt(0)
	v_add_f32_e32 v34, v34, v35
	v_lshl_add_u64 v[32:33], v[32:33], 2, s[94:95]
	global_atomic_add_f32 v[32:33], v34, off
.LBB0_1329:
	s_or_b64 exec, exec, s[8:9]
	v_or_b32_e32 v34, 32, v135
	v_or_b32_e32 v32, v34, v117
	s_waitcnt lgkmcnt(0)
	v_add_u32_e32 v35, 0xffffc000, v32
	v_cmp_gt_i32_e32 vcc, s14, v32
	v_ashrrev_i32_e32 v33, 31, v32
	v_mov_b32_e32 v38, s41
	v_cndmask_b32_e32 v36, v35, v32, vcc
	v_mov_b32_e32 v35, s43
	v_cndmask_b32_e32 v37, 0, v33, vcc
	v_cndmask_b32_e32 v39, v35, v38, vcc
	v_mov_b32_e32 v35, s42
	v_mov_b32_e32 v38, s40
	v_cndmask_b32_e32 v38, v35, v38, vcc
	v_lshlrev_b64 v[36:37], 12, v[36:37]
	v_lshl_add_u64 v[36:37], v[38:39], 0, v[36:37]
	v_lshl_add_u64 v[38:39], v[36:37], 0, v[64:65]
	v_accvgpr_read_b32 v35, a16
	v_lshlrev_b64 v[38:39], 12, v[32:33]
	v_lshl_add_u64 v[38:39], s[78:79], 0, v[38:39]
	v_mov_b32_e32 v93, v65
	v_lshl_add_u64 v[40:41], v[38:39], 0, v[64:65]
	v_lshl_add_u64 v[36:37], v[36:37], 0, v[92:93]
	v_lshl_add_u64 v[38:39], v[38:39], 0, v[92:93]
	v_add_f32_e32 v16, v16, v35
	global_store_dword v[40:41], v16, off
	v_accvgpr_read_b32 v35, a0
	v_cvt_pk_bf16_f32 v40, v16, s0
	v_subrev_u32_e32 v36, s6, v32
	v_mad_u64_u32 v[36:37], s[8:9], v36, s15, v[68:69]
	ds_write_b16 v36, v40
	v_add_f32_e32 v35, v0, v35
	v_mul_f32_e32 v0, v35, v35
	v_fmac_f32_e32 v0, v16, v16
	global_store_dword v[38:39], v35, off offset:128
	v_cvt_pk_bf16_f32 v35, v35, s0
	v_add_f32_dpp v0, v0, v0 quad_perm:[1,0,3,2] row_mask:0xf bank_mask:0xf bound_ctrl:1
	ds_write_b16 v36, v35 offset:64
	s_nop 0
	v_add_f32_dpp v0, v0, v0 quad_perm:[2,3,0,1] row_mask:0xf bank_mask:0xf bound_ctrl:1
	s_nop 1
	v_add_f32_dpp v0, v0, v0 row_half_mirror row_mask:0xf bank_mask:0xf bound_ctrl:1
	s_nop 1
	v_add_f32_dpp v0, v0, v0 row_mirror row_mask:0xf bank_mask:0xf bound_ctrl:1
	ds_bpermute_b32 v16, v118, v0
	s_and_saveexec_b64 s[8:9], s[4:5]
	s_cbranch_execz .LBB0_1331
	s_waitcnt lgkmcnt(0)
	v_add_f32_e32 v0, v0, v16
	v_lshl_add_u64 v[32:33], v[32:33], 2, s[94:95]
	global_atomic_add_f32 v[32:33], v0, off
; __device__ __forceinline__ u16 f2bf(float f) { return (u16)(pack2(f, f) & 0xffffu); }
; __device__ __forceinline__ float sum32(float v) { v = dpp_row_sum16(v); v += __shfl_xor(v, 16); return v; }
; __device__ __forceinline__ int rowmap(int e, int lane) { return (e & 3) + 8 * (e >> 2) + 4 * (lane >> 5); }
; __device__ __forceinline__ void phase4b(const Params& p, char* smem) {
;     ...
; #pragma unroll
;     for (int i = 0; i < 2; i++)
; #pragma unroll
;       for (int e = 0; e < 16; e++) {
;         const int row = m0 + wm * 64 + i * 32 + rowmap(e, lane);
;         const float* xr = xrow(p, row);
;         float sq = 0.f;
; #pragma unroll
;         for (int j = 0; j < 2; j++) {
;           const int col = n0 + wn * 64 + j * 32 + (lane & 31);
;           float v = acc[i][j][e] + xr[col];
;           X1[(size_t)row * 1024 + col] = v;
;           ((u16*)smem)[(row - m0) * 136 + (col - n0)] = f2bf(v);
;           sq += v * v;
;         }
;         sq = sum32(sq);
;         if ((lane & 31) == 0) atomicAdd(&SSQ1[row], sq);
;       }
.LBB0_1331:
	s_or_b64 exec, exec, s[8:9]
	v_or_b32_e32 v32, v34, v120
	v_add_u32_e32 v0, 0xffffc000, v32
	v_cmp_gt_i32_e32 vcc, s14, v32
	v_ashrrev_i32_e32 v33, 31, v32
	s_waitcnt lgkmcnt(0)
	v_mov_b32_e32 v16, s41
	v_cndmask_b32_e32 v36, v0, v32, vcc
	v_mov_b32_e32 v0, s43
	v_cndmask_b32_e32 v37, 0, v33, vcc
	v_cndmask_b32_e32 v39, v0, v16, vcc
	v_mov_b32_e32 v0, s42
	v_mov_b32_e32 v16, s40
	v_cndmask_b32_e32 v38, v0, v16, vcc
	v_lshlrev_b64 v[36:37], 12, v[36:37]
	v_lshl_add_u64 v[36:37], v[38:39], 0, v[36:37]
	v_lshl_add_u64 v[38:39], v[36:37], 0, v[64:65]
	v_accvgpr_read_b32 v0, a17
	v_lshlrev_b64 v[38:39], 12, v[32:33]
	v_lshl_add_u64 v[38:39], s[78:79], 0, v[38:39]
	v_lshl_add_u64 v[40:41], v[38:39], 0, v[64:65]
	v_add_f32_e32 v0, v17, v0
	global_store_dword v[40:41], v0, off
	v_lshl_add_u64 v[16:17], v[36:37], 0, v[92:93]
	v_accvgpr_read_b32 v35, a1
	v_subrev_u32_e32 v16, s6, v32
	v_mad_u64_u32 v[16:17], s[8:9], v16, s15, v[68:69]
	v_cvt_pk_bf16_f32 v36, v0, s0
	ds_write_b16 v16, v36
	v_lshl_add_u64 v[36:37], v[38:39], 0, v[92:93]
	v_add_f32_e32 v17, v1, v35
	v_mul_f32_e32 v1, v17, v17
	v_fmac_f32_e32 v1, v0, v0
	global_store_dword v[36:37], v17, off offset:128
	v_cvt_pk_bf16_f32 v17, v17, s0
	v_add_f32_dpp v0, v1, v1 quad_perm:[1,0,3,2] row_mask:0xf bank_mask:0xf bound_ctrl:1
	ds_write_b16 v16, v17 offset:64
	s_nop 0
	v_add_f32_dpp v0, v0, v0 quad_perm:[2,3,0,1] row_mask:0xf bank_mask:0xf bound_ctrl:1
	s_nop 1
	v_add_f32_dpp v0, v0, v0 row_half_mirror row_mask:0xf bank_mask:0xf bound_ctrl:1
	s_nop 1
	v_add_f32_dpp v0, v0, v0 row_mirror row_mask:0xf bank_mask:0xf bound_ctrl:1
	ds_bpermute_b32 v1, v118, v0
	s_and_saveexec_b64 s[8:9], s[4:5]
	s_cbranch_execz .LBB0_1333
	s_waitcnt lgkmcnt(0)
	v_add_f32_e32 v16, v0, v1
	v_lshl_add_u64 v[0:1], v[32:33], 2, s[94:95]
	global_atomic_add_f32 v[0:1], v16, off
.LBB0_1333:
	s_or_b64 exec, exec, s[8:9]
	v_or_b32_e32 v0, v34, v121
	v_add_u32_e32 v16, 0xffffc000, v0
	s_waitcnt lgkmcnt(0)
	v_ashrrev_i32_e32 v1, 31, v0
	v_cmp_gt_i32_e32 vcc, s14, v0
	v_mov_b32_e32 v32, s43
	v_mov_b32_e32 v33, s41
	v_cndmask_b32_e32 v17, 0, v1, vcc
	v_cndmask_b32_e32 v16, v16, v0, vcc
	v_cndmask_b32_e32 v33, v32, v33, vcc
	v_mov_b32_e32 v32, s42
	v_mov_b32_e32 v35, s40
	v_cndmask_b32_e32 v32, v32, v35, vcc
	v_lshlrev_b64 v[16:17], 12, v[16:17]
	v_lshl_add_u64 v[16:17], v[32:33], 0, v[16:17]
	v_lshl_add_u64 v[32:33], v[16:17], 0, v[64:65]
	v_accvgpr_read_b32 v35, a18
	v_lshlrev_b64 v[32:33], 12, v[0:1]
	v_lshl_add_u64 v[32:33], s[78:79], 0, v[32:33]
	v_mov_b32_e32 v93, v65
	v_lshl_add_u64 v[36:37], v[32:33], 0, v[64:65]
	v_lshl_add_u64 v[16:17], v[16:17], 0, v[92:93]
	v_lshl_add_u64 v[32:33], v[32:33], 0, v[92:93]
	v_add_f32_e32 v18, v18, v35
	global_store_dword v[36:37], v18, off
	v_accvgpr_read_b32 v16, a2
	v_subrev_u32_e32 v17, s6, v0
	v_mad_u64_u32 v[36:37], s[8:9], v17, s15, v[68:69]
	v_cvt_pk_bf16_f32 v35, v18, s0
	ds_write_b16 v36, v35
	v_add_f32_e32 v17, v2, v16
	v_mul_f32_e32 v2, v17, v17
	v_fmac_f32_e32 v2, v18, v18
	global_store_dword v[32:33], v17, off offset:128
	v_cvt_pk_bf16_f32 v17, v17, s0
	v_add_f32_dpp v2, v2, v2 quad_perm:[1,0,3,2] row_mask:0xf bank_mask:0xf bound_ctrl:1
	ds_write_b16 v36, v17 offset:64
	s_nop 0
	v_add_f32_dpp v2, v2, v2 quad_perm:[2,3,0,1] row_mask:0xf bank_mask:0xf bound_ctrl:1
	s_nop 1
	v_add_f32_dpp v2, v2, v2 row_half_mirror row_mask:0xf bank_mask:0xf bound_ctrl:1
	s_nop 1
	v_add_f32_dpp v2, v2, v2 row_mirror row_mask:0xf bank_mask:0xf bound_ctrl:1
	ds_bpermute_b32 v16, v118, v2
	s_and_saveexec_b64 s[8:9], s[4:5]
	s_cbranch_execz .LBB0_1335
	s_waitcnt lgkmcnt(0)
	v_add_f32_e32 v2, v2, v16
	v_lshl_add_u64 v[0:1], v[0:1], 2, s[94:95]
	global_atomic_add_f32 v[0:1], v2, off
.LBB0_1335:
	s_or_b64 exec, exec, s[8:9]
	v_or_b32_e32 v0, v34, v122
	v_add_u32_e32 v2, 0xffffc000, v0
	v_cmp_gt_i32_e32 vcc, s14, v0
	v_ashrrev_i32_e32 v1, 31, v0
	v_mov_b32_e32 v18, s41
	s_waitcnt lgkmcnt(0)
	v_cndmask_b32_e32 v16, v2, v0, vcc
	v_mov_b32_e32 v2, s43
	v_cndmask_b32_e32 v17, 0, v1, vcc
	v_cndmask_b32_e32 v33, v2, v18, vcc
	v_mov_b32_e32 v2, s42
	v_mov_b32_e32 v18, s40
	v_cndmask_b32_e32 v32, v2, v18, vcc
	v_lshlrev_b64 v[16:17], 12, v[16:17]
	v_lshl_add_u64 v[16:17], v[32:33], 0, v[16:17]
	v_lshl_add_u64 v[32:33], v[16:17], 0, v[64:65]
	v_accvgpr_read_b32 v2, a19
	v_lshlrev_b64 v[32:33], 12, v[0:1]
	v_lshl_add_u64 v[32:33], s[78:79], 0, v[32:33]
	v_lshl_add_u64 v[36:37], v[32:33], 0, v[64:65]
	v_lshl_add_u64 v[16:17], v[16:17], 0, v[92:93]
	v_add_f32_e32 v2, v19, v2
	global_store_dword v[36:37], v2, off
	v_accvgpr_read_b32 v18, a3
	v_subrev_u32_e32 v16, s6, v0
	v_mad_u64_u32 v[16:17], s[8:9], v16, s15, v[68:69]
	v_cvt_pk_bf16_f32 v19, v2, s0
	ds_write_b16 v16, v19
	v_add_f32_e32 v17, v3, v18
	v_mul_f32_e32 v3, v17, v17
	v_fmac_f32_e32 v3, v2, v2
	v_lshl_add_u64 v[18:19], v[32:33], 0, v[92:93]
	global_store_dword v[18:19], v17, off offset:128
	v_add_f32_dpp v2, v3, v3 quad_perm:[1,0,3,2] row_mask:0xf bank_mask:0xf bound_ctrl:1
	v_cvt_pk_bf16_f32 v17, v17, s0
	ds_write_b16 v16, v17 offset:64
	v_add_f32_dpp v2, v2, v2 quad_perm:[2,3,0,1] row_mask:0xf bank_mask:0xf bound_ctrl:1
	s_nop 1
	v_add_f32_dpp v2, v2, v2 row_half_mirror row_mask:0xf bank_mask:0xf bound_ctrl:1
	s_nop 1
	v_add_f32_dpp v2, v2, v2 row_mirror row_mask:0xf bank_mask:0xf bound_ctrl:1
	ds_bpermute_b32 v3, v118, v2
	s_and_saveexec_b64 s[8:9], s[4:5]
	s_cbranch_execz .LBB0_1337
	s_waitcnt lgkmcnt(0)
	v_add_f32_e32 v2, v2, v3
	v_lshl_add_u64 v[0:1], v[0:1], 2, s[94:95]
	global_atomic_add_f32 v[0:1], v2, off
; __device__ __forceinline__ u16 f2bf(float f) { return (u16)(pack2(f, f) & 0xffffu); }
; __device__ __forceinline__ float sum32(float v) { v = dpp_row_sum16(v); v += __shfl_xor(v, 16); return v; }
; __device__ __forceinline__ int rowmap(int e, int lane) { return (e & 3) + 8 * (e >> 2) + 4 * (lane >> 5); }
; __device__ __forceinline__ void phase4b(const Params& p, char* smem) {
;     ...
; #pragma unroll
;     for (int i = 0; i < 2; i++)
; #pragma unroll
;       for (int e = 0; e < 16; e++) {
;         const int row = m0 + wm * 64 + i * 32 + rowmap(e, lane);
;         const float* xr = xrow(p, row);
;         float sq = 0.f;
; #pragma unroll
;         for (int j = 0; j < 2; j++) {
;           const int col = n0 + wn * 64 + j * 32 + (lane & 31);
;           float v = acc[i][j][e] + xr[col];
;           X1[(size_t)row * 1024 + col] = v;
;           ((u16*)smem)[(row - m0) * 136 + (col - n0)] = f2bf(v);
;           sq += v * v;
;         }
;         sq = sum32(sq);
;         if ((lane & 31) == 0) atomicAdd(&SSQ1[row], sq);
;       }
.LBB0_1337:
	s_or_b64 exec, exec, s[8:9]
	v_or_b32_e32 v0, v34, v123
	v_add_u32_e32 v2, 0xffffc000, v0
	v_ashrrev_i32_e32 v1, 31, v0
	v_cmp_gt_i32_e32 vcc, s14, v0
	v_mov_b32_e32 v16, s43
	v_mov_b32_e32 v17, s41
	s_waitcnt lgkmcnt(0)
	v_cndmask_b32_e32 v3, 0, v1, vcc
	v_cndmask_b32_e32 v2, v2, v0, vcc
	v_cndmask_b32_e32 v17, v16, v17, vcc
	v_mov_b32_e32 v16, s42
	v_mov_b32_e32 v18, s40
	v_cndmask_b32_e32 v16, v16, v18, vcc
	v_lshlrev_b64 v[2:3], 12, v[2:3]
	v_lshl_add_u64 v[2:3], v[16:17], 0, v[2:3]
	v_lshl_add_u64 v[16:17], v[2:3], 0, v[64:65]
	v_accvgpr_read_b32 v32, a20
	v_lshlrev_b64 v[16:17], 12, v[0:1]
	v_lshl_add_u64 v[16:17], s[78:79], 0, v[16:17]
	v_mov_b32_e32 v93, v65
	v_lshl_add_u64 v[18:19], v[16:17], 0, v[64:65]
	v_lshl_add_u64 v[2:3], v[2:3], 0, v[92:93]
	v_lshl_add_u64 v[16:17], v[16:17], 0, v[92:93]
	v_add_f32_e32 v20, v20, v32
	global_store_dword v[18:19], v20, off
	v_accvgpr_read_b32 v2, a4
	v_subrev_u32_e32 v3, s6, v0
	v_mad_u64_u32 v[18:19], s[8:9], v3, s15, v[68:69]
	v_cvt_pk_bf16_f32 v32, v20, s0
	ds_write_b16 v18, v32
	v_add_f32_e32 v4, v4, v2
	v_mul_f32_e32 v2, v4, v4
	v_fmac_f32_e32 v2, v20, v20
	global_store_dword v[16:17], v4, off offset:128
	v_cvt_pk_bf16_f32 v4, v4, s0
	v_add_f32_dpp v2, v2, v2 quad_perm:[1,0,3,2] row_mask:0xf bank_mask:0xf bound_ctrl:1
	ds_write_b16 v18, v4 offset:64
	s_nop 0
	v_add_f32_dpp v2, v2, v2 quad_perm:[2,3,0,1] row_mask:0xf bank_mask:0xf bound_ctrl:1
	s_nop 1
	v_add_f32_dpp v2, v2, v2 row_half_mirror row_mask:0xf bank_mask:0xf bound_ctrl:1
	s_nop 1
	v_add_f32_dpp v2, v2, v2 row_mirror row_mask:0xf bank_mask:0xf bound_ctrl:1
	ds_bpermute_b32 v3, v118, v2
	s_and_saveexec_b64 s[8:9], s[4:5]
	s_cbranch_execz .LBB0_1339
	s_waitcnt lgkmcnt(0)
	v_add_f32_e32 v2, v2, v3
	v_lshl_add_u64 v[0:1], v[0:1], 2, s[94:95]
	global_atomic_add_f32 v[0:1], v2, off
.LBB0_1339:
	s_or_b64 exec, exec, s[8:9]
	v_or_b32_e32 v0, v34, v124
	v_add_u32_e32 v2, 0xffffc000, v0
	v_ashrrev_i32_e32 v1, 31, v0
	v_cmp_gt_i32_e32 vcc, s14, v0
	v_mov_b32_e32 v4, s43
	v_mov_b32_e32 v16, s41
	s_waitcnt lgkmcnt(0)
	v_cndmask_b32_e32 v3, 0, v1, vcc
	v_cndmask_b32_e32 v2, v2, v0, vcc
	v_cndmask_b32_e32 v17, v4, v16, vcc
	v_mov_b32_e32 v4, s42
	v_mov_b32_e32 v16, s40
	v_cndmask_b32_e32 v16, v4, v16, vcc
	v_lshlrev_b64 v[2:3], 12, v[2:3]
	v_lshl_add_u64 v[2:3], v[16:17], 0, v[2:3]
	v_lshl_add_u64 v[16:17], v[2:3], 0, v[64:65]
	v_accvgpr_read_b32 v4, a21
	v_lshlrev_b64 v[16:17], 12, v[0:1]
	v_lshl_add_u64 v[16:17], s[78:79], 0, v[16:17]
	v_lshl_add_u64 v[18:19], v[16:17], 0, v[64:65]
	v_lshl_add_u64 v[2:3], v[2:3], 0, v[92:93]
	v_add_f32_e32 v4, v21, v4
	global_store_dword v[18:19], v4, off
	v_accvgpr_read_b32 v2, a5
	v_subrev_u32_e32 v3, s6, v0
	v_mad_u64_u32 v[18:19], s[8:9], v3, s15, v[68:69]
	v_cvt_pk_bf16_f32 v20, v4, s0
	ds_write_b16 v18, v20
	v_add_f32_e32 v19, v5, v2
	v_mul_f32_e32 v2, v19, v19
	v_fmac_f32_e32 v2, v4, v4
	v_lshl_add_u64 v[4:5], v[16:17], 0, v[92:93]
	global_store_dword v[4:5], v19, off offset:128
	v_add_f32_dpp v2, v2, v2 quad_perm:[1,0,3,2] row_mask:0xf bank_mask:0xf bound_ctrl:1
	v_cvt_pk_bf16_f32 v4, v19, s0
	ds_write_b16 v18, v4 offset:64
	v_add_f32_dpp v2, v2, v2 quad_perm:[2,3,0,1] row_mask:0xf bank_mask:0xf bound_ctrl:1
	s_nop 1
	v_add_f32_dpp v2, v2, v2 row_half_mirror row_mask:0xf bank_mask:0xf bound_ctrl:1
	s_nop 1
	v_add_f32_dpp v2, v2, v2 row_mirror row_mask:0xf bank_mask:0xf bound_ctrl:1
	ds_bpermute_b32 v3, v118, v2
	s_and_saveexec_b64 s[8:9], s[4:5]
	s_cbranch_execz .LBB0_1341
	s_waitcnt lgkmcnt(0)
	v_add_f32_e32 v2, v2, v3
	v_lshl_add_u64 v[0:1], v[0:1], 2, s[94:95]
	global_atomic_add_f32 v[0:1], v2, off
.LBB0_1341:
	s_or_b64 exec, exec, s[8:9]
	v_or_b32_e32 v0, v34, v125
	v_add_u32_e32 v2, 0xffffc000, v0
	v_ashrrev_i32_e32 v1, 31, v0
	v_cmp_gt_i32_e32 vcc, s14, v0
	v_mov_b32_e32 v4, s43
	v_mov_b32_e32 v5, s41
	s_waitcnt lgkmcnt(0)
	v_cndmask_b32_e32 v3, 0, v1, vcc
	v_cndmask_b32_e32 v2, v2, v0, vcc
	v_cndmask_b32_e32 v5, v4, v5, vcc
	v_mov_b32_e32 v4, s42
	v_mov_b32_e32 v16, s40
	v_cndmask_b32_e32 v4, v4, v16, vcc
	v_lshlrev_b64 v[2:3], 12, v[2:3]
	v_lshl_add_u64 v[2:3], v[4:5], 0, v[2:3]
	v_lshl_add_u64 v[4:5], v[2:3], 0, v[64:65]
	v_accvgpr_read_b32 v18, a22
	v_lshlrev_b64 v[4:5], 12, v[0:1]
	v_lshl_add_u64 v[4:5], s[78:79], 0, v[4:5]
	v_mov_b32_e32 v93, v65
	v_lshl_add_u64 v[16:17], v[4:5], 0, v[64:65]
	v_lshl_add_u64 v[2:3], v[2:3], 0, v[92:93]
	v_lshl_add_u64 v[4:5], v[4:5], 0, v[92:93]
	v_add_f32_e32 v18, v22, v18
	global_store_dword v[16:17], v18, off
	v_accvgpr_read_b32 v2, a6
	v_subrev_u32_e32 v3, s6, v0
	v_mad_u64_u32 v[16:17], s[8:9], v3, s15, v[68:69]
	v_cvt_pk_bf16_f32 v19, v18, s0
	ds_write_b16 v16, v19
	v_add_f32_e32 v6, v6, v2
	v_mul_f32_e32 v2, v6, v6
	v_fmac_f32_e32 v2, v18, v18
	global_store_dword v[4:5], v6, off offset:128
	v_cvt_pk_bf16_f32 v4, v6, s0
	v_add_f32_dpp v2, v2, v2 quad_perm:[1,0,3,2] row_mask:0xf bank_mask:0xf bound_ctrl:1
	ds_write_b16 v16, v4 offset:64
	s_nop 0
	v_add_f32_dpp v2, v2, v2 quad_perm:[2,3,0,1] row_mask:0xf bank_mask:0xf bound_ctrl:1
	s_nop 1
	v_add_f32_dpp v2, v2, v2 row_half_mirror row_mask:0xf bank_mask:0xf bound_ctrl:1
	s_nop 1
	v_add_f32_dpp v2, v2, v2 row_mirror row_mask:0xf bank_mask:0xf bound_ctrl:1
	ds_bpermute_b32 v3, v118, v2
	s_and_saveexec_b64 s[8:9], s[4:5]
	s_cbranch_execz .LBB0_1343
	s_waitcnt lgkmcnt(0)
	v_add_f32_e32 v2, v2, v3
	v_lshl_add_u64 v[0:1], v[0:1], 2, s[94:95]
	global_atomic_add_f32 v[0:1], v2, off
; __device__ __forceinline__ u16 f2bf(float f) { return (u16)(pack2(f, f) & 0xffffu); }
; __device__ __forceinline__ float sum32(float v) { v = dpp_row_sum16(v); v += __shfl_xor(v, 16); return v; }
; __device__ __forceinline__ int rowmap(int e, int lane) { return (e & 3) + 8 * (e >> 2) + 4 * (lane >> 5); }
; __device__ __forceinline__ void phase4b(const Params& p, char* smem) {
;     ...
; #pragma unroll
;     for (int i = 0; i < 2; i++)
; #pragma unroll
;       for (int e = 0; e < 16; e++) {
;         const int row = m0 + wm * 64 + i * 32 + rowmap(e, lane);
;         const float* xr = xrow(p, row);
;         float sq = 0.f;
; #pragma unroll
;         for (int j = 0; j < 2; j++) {
;           const int col = n0 + wn * 64 + j * 32 + (lane & 31);
;           float v = acc[i][j][e] + xr[col];
;           X1[(size_t)row * 1024 + col] = v;
;           ((u16*)smem)[(row - m0) * 136 + (col - n0)] = f2bf(v);
;           sq += v * v;
;         }
;         sq = sum32(sq);
;         if ((lane & 31) == 0) atomicAdd(&SSQ1[row], sq);
;       }
.LBB0_1343:
	s_or_b64 exec, exec, s[8:9]
	v_or_b32_e32 v0, v34, v126
	v_add_u32_e32 v2, 0xffffc000, v0
	v_ashrrev_i32_e32 v1, 31, v0
	v_cmp_gt_i32_e32 vcc, s14, v0
	v_mov_b32_e32 v4, s43
	v_mov_b32_e32 v5, s41
	s_waitcnt lgkmcnt(0)
	v_cndmask_b32_e32 v3, 0, v1, vcc
	v_cndmask_b32_e32 v2, v2, v0, vcc
	v_cndmask_b32_e32 v5, v4, v5, vcc
	v_mov_b32_e32 v4, s42
	v_mov_b32_e32 v6, s40
	v_cndmask_b32_e32 v4, v4, v6, vcc
	v_lshlrev_b64 v[2:3], 12, v[2:3]
	v_lshl_add_u64 v[2:3], v[4:5], 0, v[2:3]
	v_lshl_add_u64 v[4:5], v[2:3], 0, v[64:65]
	v_accvgpr_read_b32 v6, a23
	v_lshlrev_b64 v[4:5], 12, v[0:1]
	v_lshl_add_u64 v[4:5], s[78:79], 0, v[4:5]
	v_lshl_add_u64 v[16:17], v[4:5], 0, v[64:65]
	v_lshl_add_u64 v[2:3], v[2:3], 0, v[92:93]
	v_lshl_add_u64 v[4:5], v[4:5], 0, v[92:93]
	v_add_f32_e32 v6, v23, v6
	global_store_dword v[16:17], v6, off
	v_accvgpr_read_b32 v2, a7
	v_subrev_u32_e32 v3, s6, v0
	v_mad_u64_u32 v[16:17], s[8:9], v3, s15, v[68:69]
	v_cvt_pk_bf16_f32 v18, v6, s0
	ds_write_b16 v16, v18
	v_add_f32_e32 v7, v7, v2
	v_mul_f32_e32 v2, v7, v7
	v_fmac_f32_e32 v2, v6, v6
	global_store_dword v[4:5], v7, off offset:128
	v_cvt_pk_bf16_f32 v4, v7, s0
	v_add_f32_dpp v2, v2, v2 quad_perm:[1,0,3,2] row_mask:0xf bank_mask:0xf bound_ctrl:1
	ds_write_b16 v16, v4 offset:64
	s_nop 0
	v_add_f32_dpp v2, v2, v2 quad_perm:[2,3,0,1] row_mask:0xf bank_mask:0xf bound_ctrl:1
	s_nop 1
	v_add_f32_dpp v2, v2, v2 row_half_mirror row_mask:0xf bank_mask:0xf bound_ctrl:1
	s_nop 1
	v_add_f32_dpp v2, v2, v2 row_mirror row_mask:0xf bank_mask:0xf bound_ctrl:1
	ds_bpermute_b32 v3, v118, v2
	s_and_saveexec_b64 s[8:9], s[4:5]
	s_cbranch_execz .LBB0_1345
	s_waitcnt lgkmcnt(0)
	v_add_f32_e32 v2, v2, v3
	v_lshl_add_u64 v[0:1], v[0:1], 2, s[94:95]
	global_atomic_add_f32 v[0:1], v2, off
.LBB0_1345:
	s_or_b64 exec, exec, s[8:9]
	v_or_b32_e32 v0, v34, v127
	v_add_u32_e32 v2, 0xffffc000, v0
	v_ashrrev_i32_e32 v1, 31, v0
	v_cmp_gt_i32_e32 vcc, s14, v0
	v_mov_b32_e32 v4, s43
	v_mov_b32_e32 v5, s41
	s_waitcnt lgkmcnt(0)
	v_cndmask_b32_e32 v3, 0, v1, vcc
	v_cndmask_b32_e32 v2, v2, v0, vcc
	v_cndmask_b32_e32 v5, v4, v5, vcc
	v_mov_b32_e32 v4, s42
	v_mov_b32_e32 v6, s40
	v_cndmask_b32_e32 v4, v4, v6, vcc
	v_lshlrev_b64 v[2:3], 12, v[2:3]
	v_lshl_add_u64 v[2:3], v[4:5], 0, v[2:3]
	v_lshl_add_u64 v[4:5], v[2:3], 0, v[64:65]
	v_accvgpr_read_b32 v16, a24
	v_lshlrev_b64 v[4:5], 12, v[0:1]
	v_lshl_add_u64 v[4:5], s[78:79], 0, v[4:5]
	v_mov_b32_e32 v93, v65
	v_lshl_add_u64 v[6:7], v[4:5], 0, v[64:65]
	v_lshl_add_u64 v[2:3], v[2:3], 0, v[92:93]
	v_lshl_add_u64 v[4:5], v[4:5], 0, v[92:93]
	v_add_f32_e32 v16, v24, v16
	global_store_dword v[6:7], v16, off
	v_accvgpr_read_b32 v2, a8
	v_subrev_u32_e32 v3, s6, v0
	v_mad_u64_u32 v[6:7], s[8:9], v3, s15, v[68:69]
	v_cvt_pk_bf16_f32 v17, v16, s0
	ds_write_b16 v6, v17
	v_add_f32_e32 v7, v8, v2
	v_mul_f32_e32 v2, v7, v7
	v_fmac_f32_e32 v2, v16, v16
	global_store_dword v[4:5], v7, off offset:128
	v_cvt_pk_bf16_f32 v4, v7, s0
	v_add_f32_dpp v2, v2, v2 quad_perm:[1,0,3,2] row_mask:0xf bank_mask:0xf bound_ctrl:1
	ds_write_b16 v6, v4 offset:64
	s_nop 0
	v_add_f32_dpp v2, v2, v2 quad_perm:[2,3,0,1] row_mask:0xf bank_mask:0xf bound_ctrl:1
	s_nop 1
	v_add_f32_dpp v2, v2, v2 row_half_mirror row_mask:0xf bank_mask:0xf bound_ctrl:1
	s_nop 1
	v_add_f32_dpp v2, v2, v2 row_mirror row_mask:0xf bank_mask:0xf bound_ctrl:1
	ds_bpermute_b32 v3, v118, v2
	s_and_saveexec_b64 s[8:9], s[4:5]
	s_cbranch_execz .LBB0_1347
	s_waitcnt lgkmcnt(0)
	v_add_f32_e32 v2, v2, v3
	v_lshl_add_u64 v[0:1], v[0:1], 2, s[94:95]
	global_atomic_add_f32 v[0:1], v2, off
.LBB0_1347:
	s_or_b64 exec, exec, s[8:9]
	v_or_b32_e32 v0, v34, v128
	v_add_u32_e32 v2, 0xffffc000, v0
	v_ashrrev_i32_e32 v1, 31, v0
	v_cmp_gt_i32_e32 vcc, s14, v0
	v_mov_b32_e32 v4, s43
	v_mov_b32_e32 v5, s41
	s_waitcnt lgkmcnt(0)
	v_cndmask_b32_e32 v3, 0, v1, vcc
	v_cndmask_b32_e32 v2, v2, v0, vcc
	v_cndmask_b32_e32 v5, v4, v5, vcc
	v_mov_b32_e32 v4, s42
	v_mov_b32_e32 v6, s40
	v_cndmask_b32_e32 v4, v4, v6, vcc
	v_lshlrev_b64 v[2:3], 12, v[2:3]
	v_lshl_add_u64 v[2:3], v[4:5], 0, v[2:3]
	v_lshl_add_u64 v[4:5], v[2:3], 0, v[64:65]
	v_accvgpr_read_b32 v8, a25
	v_lshlrev_b64 v[4:5], 12, v[0:1]
	v_lshl_add_u64 v[4:5], s[78:79], 0, v[4:5]
	v_lshl_add_u64 v[6:7], v[4:5], 0, v[64:65]
	v_lshl_add_u64 v[2:3], v[2:3], 0, v[92:93]
	v_lshl_add_u64 v[4:5], v[4:5], 0, v[92:93]
	v_add_f32_e32 v8, v25, v8
	global_store_dword v[6:7], v8, off
	v_accvgpr_read_b32 v2, a9
	v_subrev_u32_e32 v3, s6, v0
	v_mad_u64_u32 v[6:7], s[8:9], v3, s15, v[68:69]
	v_cvt_pk_bf16_f32 v16, v8, s0
	ds_write_b16 v6, v16
	v_add_f32_e32 v7, v9, v2
	v_mul_f32_e32 v2, v7, v7
	v_fmac_f32_e32 v2, v8, v8
	global_store_dword v[4:5], v7, off offset:128
	v_cvt_pk_bf16_f32 v4, v7, s0
	v_add_f32_dpp v2, v2, v2 quad_perm:[1,0,3,2] row_mask:0xf bank_mask:0xf bound_ctrl:1
	ds_write_b16 v6, v4 offset:64
	s_nop 0
	v_add_f32_dpp v2, v2, v2 quad_perm:[2,3,0,1] row_mask:0xf bank_mask:0xf bound_ctrl:1
	s_nop 1
	v_add_f32_dpp v2, v2, v2 row_half_mirror row_mask:0xf bank_mask:0xf bound_ctrl:1
	s_nop 1
	v_add_f32_dpp v2, v2, v2 row_mirror row_mask:0xf bank_mask:0xf bound_ctrl:1
	ds_bpermute_b32 v3, v118, v2
	s_and_saveexec_b64 s[8:9], s[4:5]
	s_cbranch_execz .LBB0_1349
	s_waitcnt lgkmcnt(0)
	v_add_f32_e32 v2, v2, v3
	v_lshl_add_u64 v[0:1], v[0:1], 2, s[94:95]
	global_atomic_add_f32 v[0:1], v2, off
; __device__ __forceinline__ u16 f2bf(float f) { return (u16)(pack2(f, f) & 0xffffu); }
; __device__ __forceinline__ float sum32(float v) { v = dpp_row_sum16(v); v += __shfl_xor(v, 16); return v; }
; __device__ __forceinline__ int rowmap(int e, int lane) { return (e & 3) + 8 * (e >> 2) + 4 * (lane >> 5); }
; __device__ __forceinline__ void phase4b(const Params& p, char* smem) {
;     ...
; #pragma unroll
;     for (int i = 0; i < 2; i++)
; #pragma unroll
;       for (int e = 0; e < 16; e++) {
;         const int row = m0 + wm * 64 + i * 32 + rowmap(e, lane);
;         const float* xr = xrow(p, row);
;         float sq = 0.f;
; #pragma unroll
;         for (int j = 0; j < 2; j++) {
;           const int col = n0 + wn * 64 + j * 32 + (lane & 31);
;           float v = acc[i][j][e] + xr[col];
;           X1[(size_t)row * 1024 + col] = v;
;           ((u16*)smem)[(row - m0) * 136 + (col - n0)] = f2bf(v);
;           sq += v * v;
;         }
;         sq = sum32(sq);
;         if ((lane & 31) == 0) atomicAdd(&SSQ1[row], sq);
;       }
.LBB0_1349:
	s_or_b64 exec, exec, s[8:9]
	v_or_b32_e32 v0, v34, v129
	v_add_u32_e32 v2, 0xffffc000, v0
	v_ashrrev_i32_e32 v1, 31, v0
	v_cmp_gt_i32_e32 vcc, s14, v0
	v_mov_b32_e32 v4, s43
	v_mov_b32_e32 v5, s41
	s_waitcnt lgkmcnt(0)
	v_cndmask_b32_e32 v3, 0, v1, vcc
	v_cndmask_b32_e32 v2, v2, v0, vcc
	v_cndmask_b32_e32 v5, v4, v5, vcc
	v_mov_b32_e32 v4, s42
	v_mov_b32_e32 v6, s40
	v_cndmask_b32_e32 v4, v4, v6, vcc
	v_lshlrev_b64 v[2:3], 12, v[2:3]
	v_lshl_add_u64 v[2:3], v[4:5], 0, v[2:3]
	v_lshl_add_u64 v[4:5], v[2:3], 0, v[64:65]
	v_accvgpr_read_b32 v8, a26
	v_lshlrev_b64 v[4:5], 12, v[0:1]
	v_lshl_add_u64 v[4:5], s[78:79], 0, v[4:5]
	v_mov_b32_e32 v93, v65
	v_lshl_add_u64 v[6:7], v[4:5], 0, v[64:65]
	v_lshl_add_u64 v[2:3], v[2:3], 0, v[92:93]
	v_lshl_add_u64 v[4:5], v[4:5], 0, v[92:93]
	v_add_f32_e32 v8, v26, v8
	global_store_dword v[6:7], v8, off
	v_accvgpr_read_b32 v2, a10
	v_subrev_u32_e32 v3, s6, v0
	v_mad_u64_u32 v[6:7], s[8:9], v3, s15, v[68:69]
	v_cvt_pk_bf16_f32 v9, v8, s0
	ds_write_b16 v6, v9
	v_add_f32_e32 v7, v10, v2
	v_mul_f32_e32 v2, v7, v7
	v_fmac_f32_e32 v2, v8, v8
	global_store_dword v[4:5], v7, off offset:128
	v_cvt_pk_bf16_f32 v4, v7, s0
	v_add_f32_dpp v2, v2, v2 quad_perm:[1,0,3,2] row_mask:0xf bank_mask:0xf bound_ctrl:1
	ds_write_b16 v6, v4 offset:64
	s_nop 0
	v_add_f32_dpp v2, v2, v2 quad_perm:[2,3,0,1] row_mask:0xf bank_mask:0xf bound_ctrl:1
	s_nop 1
	v_add_f32_dpp v2, v2, v2 row_half_mirror row_mask:0xf bank_mask:0xf bound_ctrl:1
	s_nop 1
	v_add_f32_dpp v2, v2, v2 row_mirror row_mask:0xf bank_mask:0xf bound_ctrl:1
	ds_bpermute_b32 v3, v118, v2
	s_and_saveexec_b64 s[8:9], s[4:5]
	s_cbranch_execz .LBB0_1351
	s_waitcnt lgkmcnt(0)
	v_add_f32_e32 v2, v2, v3
	v_lshl_add_u64 v[0:1], v[0:1], 2, s[94:95]
	global_atomic_add_f32 v[0:1], v2, off
.LBB0_1351:
	s_or_b64 exec, exec, s[8:9]
	v_or_b32_e32 v0, v34, v130
	v_add_u32_e32 v2, 0xffffc000, v0
	v_ashrrev_i32_e32 v1, 31, v0
	v_cmp_gt_i32_e32 vcc, s14, v0
	v_mov_b32_e32 v4, s43
	v_mov_b32_e32 v5, s41
	s_waitcnt lgkmcnt(0)
	v_cndmask_b32_e32 v3, 0, v1, vcc
	v_cndmask_b32_e32 v2, v2, v0, vcc
	v_cndmask_b32_e32 v5, v4, v5, vcc
	v_mov_b32_e32 v4, s42
	v_mov_b32_e32 v6, s40
	v_cndmask_b32_e32 v4, v4, v6, vcc
	v_lshlrev_b64 v[2:3], 12, v[2:3]
	v_lshl_add_u64 v[2:3], v[4:5], 0, v[2:3]
	v_lshl_add_u64 v[4:5], v[2:3], 0, v[64:65]
	v_accvgpr_read_b32 v8, a27
	v_lshlrev_b64 v[4:5], 12, v[0:1]
	v_lshl_add_u64 v[4:5], s[78:79], 0, v[4:5]
	v_lshl_add_u64 v[6:7], v[4:5], 0, v[64:65]
	v_lshl_add_u64 v[2:3], v[2:3], 0, v[92:93]
	v_lshl_add_u64 v[4:5], v[4:5], 0, v[92:93]
	v_add_f32_e32 v8, v27, v8
	global_store_dword v[6:7], v8, off
	v_accvgpr_read_b32 v2, a11
	v_subrev_u32_e32 v3, s6, v0
	v_mad_u64_u32 v[6:7], s[8:9], v3, s15, v[68:69]
	v_cvt_pk_bf16_f32 v9, v8, s0
	ds_write_b16 v6, v9
	v_add_f32_e32 v7, v11, v2
	v_mul_f32_e32 v2, v7, v7
	v_fmac_f32_e32 v2, v8, v8
	global_store_dword v[4:5], v7, off offset:128
	v_cvt_pk_bf16_f32 v4, v7, s0
	v_add_f32_dpp v2, v2, v2 quad_perm:[1,0,3,2] row_mask:0xf bank_mask:0xf bound_ctrl:1
	ds_write_b16 v6, v4 offset:64
	s_nop 0
	v_add_f32_dpp v2, v2, v2 quad_perm:[2,3,0,1] row_mask:0xf bank_mask:0xf bound_ctrl:1
	s_nop 1
	v_add_f32_dpp v2, v2, v2 row_half_mirror row_mask:0xf bank_mask:0xf bound_ctrl:1
	s_nop 1
	v_add_f32_dpp v2, v2, v2 row_mirror row_mask:0xf bank_mask:0xf bound_ctrl:1
	ds_bpermute_b32 v3, v118, v2
	s_and_saveexec_b64 s[8:9], s[4:5]
	s_cbranch_execz .LBB0_1353
	s_waitcnt lgkmcnt(0)
	v_add_f32_e32 v2, v2, v3
	v_lshl_add_u64 v[0:1], v[0:1], 2, s[94:95]
	global_atomic_add_f32 v[0:1], v2, off
.LBB0_1353:
	s_or_b64 exec, exec, s[8:9]
	v_or_b32_e32 v0, v34, v131
	v_add_u32_e32 v2, 0xffffc000, v0
	v_ashrrev_i32_e32 v1, 31, v0
	v_cmp_gt_i32_e32 vcc, s14, v0
	v_mov_b32_e32 v4, s43
	v_mov_b32_e32 v5, s41
	s_waitcnt lgkmcnt(0)
	v_cndmask_b32_e32 v3, 0, v1, vcc
	v_cndmask_b32_e32 v2, v2, v0, vcc
	v_cndmask_b32_e32 v5, v4, v5, vcc
	v_mov_b32_e32 v4, s42
	v_mov_b32_e32 v6, s40
	v_cndmask_b32_e32 v4, v4, v6, vcc
	v_lshlrev_b64 v[2:3], 12, v[2:3]
	v_lshl_add_u64 v[2:3], v[4:5], 0, v[2:3]
	v_lshl_add_u64 v[4:5], v[2:3], 0, v[64:65]
	v_accvgpr_read_b32 v8, a28
	v_lshlrev_b64 v[4:5], 12, v[0:1]
	v_lshl_add_u64 v[4:5], s[78:79], 0, v[4:5]
	v_mov_b32_e32 v93, v65
	v_lshl_add_u64 v[6:7], v[4:5], 0, v[64:65]
	v_lshl_add_u64 v[2:3], v[2:3], 0, v[92:93]
	v_lshl_add_u64 v[4:5], v[4:5], 0, v[92:93]
	v_add_f32_e32 v8, v28, v8
	global_store_dword v[6:7], v8, off
	v_accvgpr_read_b32 v2, a12
	v_subrev_u32_e32 v3, s6, v0
	v_mad_u64_u32 v[6:7], s[8:9], v3, s15, v[68:69]
	v_cvt_pk_bf16_f32 v9, v8, s0
	ds_write_b16 v6, v9
	v_add_f32_e32 v7, v12, v2
	v_mul_f32_e32 v2, v7, v7
	v_fmac_f32_e32 v2, v8, v8
	global_store_dword v[4:5], v7, off offset:128
	v_cvt_pk_bf16_f32 v4, v7, s0
	v_add_f32_dpp v2, v2, v2 quad_perm:[1,0,3,2] row_mask:0xf bank_mask:0xf bound_ctrl:1
	ds_write_b16 v6, v4 offset:64
	s_nop 0
	v_add_f32_dpp v2, v2, v2 quad_perm:[2,3,0,1] row_mask:0xf bank_mask:0xf bound_ctrl:1
	s_nop 1
	v_add_f32_dpp v2, v2, v2 row_half_mirror row_mask:0xf bank_mask:0xf bound_ctrl:1
	s_nop 1
	v_add_f32_dpp v2, v2, v2 row_mirror row_mask:0xf bank_mask:0xf bound_ctrl:1
	ds_bpermute_b32 v3, v118, v2
	s_and_saveexec_b64 s[8:9], s[4:5]
	s_cbranch_execz .LBB0_1355
	s_waitcnt lgkmcnt(0)
	v_add_f32_e32 v2, v2, v3
	v_lshl_add_u64 v[0:1], v[0:1], 2, s[94:95]
	global_atomic_add_f32 v[0:1], v2, off
; __device__ __forceinline__ u16 f2bf(float f) { return (u16)(pack2(f, f) & 0xffffu); }
; __device__ __forceinline__ float sum32(float v) { v = dpp_row_sum16(v); v += __shfl_xor(v, 16); return v; }
; __device__ __forceinline__ int rowmap(int e, int lane) { return (e & 3) + 8 * (e >> 2) + 4 * (lane >> 5); }
; __device__ __forceinline__ void phase4b(const Params& p, char* smem) {
;     ...
; #pragma unroll
;     for (int i = 0; i < 2; i++)
; #pragma unroll
;       for (int e = 0; e < 16; e++) {
;         const int row = m0 + wm * 64 + i * 32 + rowmap(e, lane);
;         const float* xr = xrow(p, row);
;         float sq = 0.f;
; #pragma unroll
;         for (int j = 0; j < 2; j++) {
;           const int col = n0 + wn * 64 + j * 32 + (lane & 31);
;           float v = acc[i][j][e] + xr[col];
;           X1[(size_t)row * 1024 + col] = v;
;           ((u16*)smem)[(row - m0) * 136 + (col - n0)] = f2bf(v);
;           sq += v * v;
;         }
;         sq = sum32(sq);
;         if ((lane & 31) == 0) atomicAdd(&SSQ1[row], sq);
;       }
.LBB0_1355:
	s_or_b64 exec, exec, s[8:9]
	v_or_b32_e32 v0, v34, v132
	v_add_u32_e32 v2, 0xffffc000, v0
	v_ashrrev_i32_e32 v1, 31, v0
	v_cmp_gt_i32_e32 vcc, s14, v0
	v_mov_b32_e32 v4, s43
	v_mov_b32_e32 v5, s41
	s_waitcnt lgkmcnt(0)
	v_cndmask_b32_e32 v3, 0, v1, vcc
	v_cndmask_b32_e32 v2, v2, v0, vcc
	v_cndmask_b32_e32 v5, v4, v5, vcc
	v_mov_b32_e32 v4, s42
	v_mov_b32_e32 v6, s40
	v_cndmask_b32_e32 v4, v4, v6, vcc
	v_lshlrev_b64 v[2:3], 12, v[2:3]
	v_lshl_add_u64 v[2:3], v[4:5], 0, v[2:3]
	v_lshl_add_u64 v[4:5], v[2:3], 0, v[64:65]
	v_accvgpr_read_b32 v8, a29
	v_lshlrev_b64 v[4:5], 12, v[0:1]
	v_lshl_add_u64 v[4:5], s[78:79], 0, v[4:5]
	v_lshl_add_u64 v[6:7], v[4:5], 0, v[64:65]
	v_lshl_add_u64 v[2:3], v[2:3], 0, v[92:93]
	v_lshl_add_u64 v[4:5], v[4:5], 0, v[92:93]
	v_add_f32_e32 v8, v29, v8
	global_store_dword v[6:7], v8, off
	v_accvgpr_read_b32 v2, a13
	v_subrev_u32_e32 v3, s6, v0
	v_mad_u64_u32 v[6:7], s[8:9], v3, s15, v[68:69]
	v_cvt_pk_bf16_f32 v9, v8, s0
	ds_write_b16 v6, v9
	v_add_f32_e32 v7, v13, v2
	v_mul_f32_e32 v2, v7, v7
	v_fmac_f32_e32 v2, v8, v8
	global_store_dword v[4:5], v7, off offset:128
	v_cvt_pk_bf16_f32 v4, v7, s0
	v_add_f32_dpp v2, v2, v2 quad_perm:[1,0,3,2] row_mask:0xf bank_mask:0xf bound_ctrl:1
	ds_write_b16 v6, v4 offset:64
	s_nop 0
	v_add_f32_dpp v2, v2, v2 quad_perm:[2,3,0,1] row_mask:0xf bank_mask:0xf bound_ctrl:1
	s_nop 1
	v_add_f32_dpp v2, v2, v2 row_half_mirror row_mask:0xf bank_mask:0xf bound_ctrl:1
	s_nop 1
	v_add_f32_dpp v2, v2, v2 row_mirror row_mask:0xf bank_mask:0xf bound_ctrl:1
	ds_bpermute_b32 v3, v118, v2
	s_and_saveexec_b64 s[8:9], s[4:5]
	s_cbranch_execz .LBB0_1357
	s_waitcnt lgkmcnt(0)
	v_add_f32_e32 v2, v2, v3
	v_lshl_add_u64 v[0:1], v[0:1], 2, s[94:95]
	global_atomic_add_f32 v[0:1], v2, off
.LBB0_1357:
	s_or_b64 exec, exec, s[8:9]
	v_or_b32_e32 v0, v34, v133
	v_add_u32_e32 v2, 0xffffc000, v0
	v_ashrrev_i32_e32 v1, 31, v0
	v_cmp_gt_i32_e32 vcc, s14, v0
	v_mov_b32_e32 v4, s43
	v_mov_b32_e32 v5, s41
	s_waitcnt lgkmcnt(0)
	v_cndmask_b32_e32 v3, 0, v1, vcc
	v_cndmask_b32_e32 v2, v2, v0, vcc
	v_cndmask_b32_e32 v5, v4, v5, vcc
	v_mov_b32_e32 v4, s42
	v_mov_b32_e32 v6, s40
	v_cndmask_b32_e32 v4, v4, v6, vcc
	v_lshlrev_b64 v[2:3], 12, v[2:3]
	v_lshl_add_u64 v[2:3], v[4:5], 0, v[2:3]
	v_lshl_add_u64 v[4:5], v[2:3], 0, v[64:65]
	v_accvgpr_read_b32 v8, a30
	v_lshlrev_b64 v[4:5], 12, v[0:1]
	v_lshl_add_u64 v[4:5], s[78:79], 0, v[4:5]
	v_mov_b32_e32 v93, v65
	v_lshl_add_u64 v[6:7], v[4:5], 0, v[64:65]
	v_lshl_add_u64 v[2:3], v[2:3], 0, v[92:93]
	v_lshl_add_u64 v[4:5], v[4:5], 0, v[92:93]
	v_add_f32_e32 v8, v30, v8
	global_store_dword v[6:7], v8, off
	v_accvgpr_read_b32 v2, a14
	v_subrev_u32_e32 v3, s6, v0
	v_mad_u64_u32 v[6:7], s[8:9], v3, s15, v[68:69]
	v_cvt_pk_bf16_f32 v9, v8, s0
	ds_write_b16 v6, v9
	v_add_f32_e32 v7, v14, v2
	v_mul_f32_e32 v2, v7, v7
	v_fmac_f32_e32 v2, v8, v8
	global_store_dword v[4:5], v7, off offset:128
	v_cvt_pk_bf16_f32 v4, v7, s0
	v_add_f32_dpp v2, v2, v2 quad_perm:[1,0,3,2] row_mask:0xf bank_mask:0xf bound_ctrl:1
	ds_write_b16 v6, v4 offset:64
	s_nop 0
	v_add_f32_dpp v2, v2, v2 quad_perm:[2,3,0,1] row_mask:0xf bank_mask:0xf bound_ctrl:1
	s_nop 1
	v_add_f32_dpp v2, v2, v2 row_half_mirror row_mask:0xf bank_mask:0xf bound_ctrl:1
	s_nop 1
	v_add_f32_dpp v2, v2, v2 row_mirror row_mask:0xf bank_mask:0xf bound_ctrl:1
	ds_bpermute_b32 v3, v118, v2
	s_and_saveexec_b64 s[8:9], s[4:5]
	s_cbranch_execz .LBB0_1359
	s_waitcnt lgkmcnt(0)
	v_add_f32_e32 v2, v2, v3
	v_lshl_add_u64 v[0:1], v[0:1], 2, s[94:95]
	global_atomic_add_f32 v[0:1], v2, off
.LBB0_1359:
	s_or_b64 exec, exec, s[8:9]
	v_or_b32_e32 v0, v34, v134
	v_add_u32_e32 v2, 0xffffc000, v0
	v_ashrrev_i32_e32 v1, 31, v0
	v_cmp_gt_i32_e32 vcc, s14, v0
	v_mov_b32_e32 v4, s43
	v_mov_b32_e32 v5, s41
	s_waitcnt lgkmcnt(0)
	v_cndmask_b32_e32 v3, 0, v1, vcc
	v_cndmask_b32_e32 v2, v2, v0, vcc
	v_cndmask_b32_e32 v5, v4, v5, vcc
	v_mov_b32_e32 v4, s42
	v_mov_b32_e32 v6, s40
	v_cndmask_b32_e32 v4, v4, v6, vcc
	v_lshlrev_b64 v[2:3], 12, v[2:3]
	v_lshl_add_u64 v[2:3], v[4:5], 0, v[2:3]
	v_lshl_add_u64 v[4:5], v[2:3], 0, v[64:65]
	v_accvgpr_read_b32 v8, a31
	v_lshlrev_b64 v[4:5], 12, v[0:1]
	v_lshl_add_u64 v[4:5], s[78:79], 0, v[4:5]
	v_lshl_add_u64 v[6:7], v[4:5], 0, v[64:65]
	v_lshl_add_u64 v[2:3], v[2:3], 0, v[92:93]
	v_lshl_add_u64 v[4:5], v[4:5], 0, v[92:93]
	v_add_f32_e32 v8, v31, v8
	global_store_dword v[6:7], v8, off
	v_accvgpr_read_b32 v2, a15
	v_subrev_u32_e32 v3, s6, v0
	v_mad_u64_u32 v[6:7], s[8:9], v3, s15, v[68:69]
	v_cvt_pk_bf16_f32 v9, v8, s0
	ds_write_b16 v6, v9
	v_add_f32_e32 v7, v15, v2
	v_mul_f32_e32 v2, v7, v7
	v_fmac_f32_e32 v2, v8, v8
	global_store_dword v[4:5], v7, off offset:128
	v_cvt_pk_bf16_f32 v4, v7, s0
	v_add_f32_dpp v2, v2, v2 quad_perm:[1,0,3,2] row_mask:0xf bank_mask:0xf bound_ctrl:1
	ds_write_b16 v6, v4 offset:64
	s_nop 0
	v_add_f32_dpp v2, v2, v2 quad_perm:[2,3,0,1] row_mask:0xf bank_mask:0xf bound_ctrl:1
	s_nop 1
	v_add_f32_dpp v2, v2, v2 row_half_mirror row_mask:0xf bank_mask:0xf bound_ctrl:1
	s_nop 1
	v_add_f32_dpp v2, v2, v2 row_mirror row_mask:0xf bank_mask:0xf bound_ctrl:1
	ds_bpermute_b32 v3, v118, v2
	s_and_saveexec_b64 s[8:9], s[4:5]
	s_cbranch_execz .LBB0_1290
	s_waitcnt lgkmcnt(0)
	v_add_f32_e32 v2, v2, v3
	v_lshl_add_u64 v[0:1], v[0:1], 2, s[94:95]
	global_atomic_add_f32 v[0:1], v2, off
	s_branch .LBB0_1290
